# K-loops: removed the s_setprio 0/1 pair in the middle of each 32-MFMA block
# speedup vs baseline: 1.0490x; 1.0022x over previous
.LBB0_244:
	ds_read_b128 v[146:149], v161
	ds_read_b128 v[150:153], v161 offset:1024
	ds_read_b128 v[154:157], v161 offset:2048
	ds_read_b128 v[164:167], v161 offset:3072
	ds_read_b128 v[168:171], v162
	ds_read_b128 v[172:175], v162 offset:1024
	ds_read_b128 v[176:179], v162 offset:2048
	ds_read_b128 v[180:183], v162 offset:3072
	s_add_u32 s7, s40, 0xfffc0080
	s_addc_u32 s9, s41, -1
	s_cmp_eq_u32 s5, 12
	s_cselect_b32 s45, s29, s9
	s_cselect_b32 s44, s28, s7
	s_cselect_b32 s43, s39, s3
	s_cselect_b32 s42, s38, s2
	v_lshl_add_u64 v[218:219], s[40:41], 0, v[138:139]
	s_add_i32 m0, s51, 0xc000
	ds_read_b128 v[184:187], v163
	ds_read_b128 v[188:191], v163 offset:1024
	ds_read_b128 v[194:197], v163 offset:2048
	ds_read_b128 v[198:201], v163 offset:3072
	ds_read_b128 v[202:205], v163 offset:4096
	ds_read_b128 v[206:209], v163 offset:5120
	ds_read_b128 v[210:213], v163 offset:6144
	ds_read_b128 v[214:217], v163 offset:7168
	global_load_lds_dwordx4 v[218:219], off
	v_lshl_add_u64 v[218:219], s[40:41], 0, v[140:141]
	s_add_i32 m0, s51, 0xe000
	s_nop 0
	global_load_lds_dwordx4 v[218:219], off
	s_waitcnt vmcnt(8)
	s_waitcnt lgkmcnt(0)
	s_barrier
	s_setprio 1
	s_waitcnt lgkmcnt(0)
	v_mfma_f32_16x16x32_bf16 v[124:127], v[146:149], v[184:187], v[124:127]
	v_mfma_f32_16x16x32_bf16 v[120:123], v[154:157], v[184:187], v[120:123]
	v_mfma_f32_16x16x32_bf16 v[108:111], v[146:149], v[194:197], v[108:111]
	v_mfma_f32_16x16x32_bf16 v[104:107], v[154:157], v[194:197], v[104:107]
	v_mfma_f32_16x16x32_bf16 v[92:95], v[146:149], v[202:205], v[92:95]
	v_mfma_f32_16x16x32_bf16 v[88:91], v[154:157], v[202:205], v[88:91]
	v_mfma_f32_16x16x32_bf16 v[76:79], v[146:149], v[210:213], v[76:79]
	v_mfma_f32_16x16x32_bf16 v[72:75], v[154:157], v[210:213], v[72:75]
	v_mfma_f32_16x16x32_bf16 v[124:127], v[150:153], v[188:191], v[124:127]
	v_mfma_f32_16x16x32_bf16 v[120:123], v[164:167], v[188:191], v[120:123]
	v_mfma_f32_16x16x32_bf16 v[108:111], v[150:153], v[198:201], v[108:111]
	v_mfma_f32_16x16x32_bf16 v[104:107], v[164:167], v[198:201], v[104:107]
	v_mfma_f32_16x16x32_bf16 v[92:95], v[150:153], v[206:209], v[92:95]
	v_mfma_f32_16x16x32_bf16 v[88:91], v[164:167], v[206:209], v[88:91]
	v_mfma_f32_16x16x32_bf16 v[76:79], v[150:153], v[214:217], v[76:79]
	v_mfma_f32_16x16x32_bf16 v[72:75], v[164:167], v[214:217], v[72:75]
	v_mfma_f32_16x16x32_bf16 v[116:119], v[168:171], v[184:187], v[116:119]
	v_mfma_f32_16x16x32_bf16 v[112:115], v[176:179], v[184:187], v[112:115]
	v_mfma_f32_16x16x32_bf16 v[100:103], v[168:171], v[194:197], v[100:103]
	v_mfma_f32_16x16x32_bf16 v[96:99], v[176:179], v[194:197], v[96:99]
	v_mfma_f32_16x16x32_bf16 v[84:87], v[168:171], v[202:205], v[84:87]
	v_mfma_f32_16x16x32_bf16 v[80:83], v[176:179], v[202:205], v[80:83]
	v_mfma_f32_16x16x32_bf16 v[68:71], v[168:171], v[210:213], v[68:71]
	v_mfma_f32_16x16x32_bf16 v[64:67], v[176:179], v[210:213], v[64:67]
	v_mfma_f32_16x16x32_bf16 v[116:119], v[172:175], v[188:191], v[116:119]
	v_mfma_f32_16x16x32_bf16 v[112:115], v[180:183], v[188:191], v[112:115]
	v_mfma_f32_16x16x32_bf16 v[100:103], v[172:175], v[198:201], v[100:103]
	v_mfma_f32_16x16x32_bf16 v[96:99], v[180:183], v[198:201], v[96:99]
	v_mfma_f32_16x16x32_bf16 v[84:87], v[172:175], v[206:209], v[84:87]
	v_mfma_f32_16x16x32_bf16 v[80:83], v[180:183], v[206:209], v[80:83]
	v_mfma_f32_16x16x32_bf16 v[68:71], v[172:175], v[214:217], v[68:71]
	v_mfma_f32_16x16x32_bf16 v[64:67], v[180:183], v[214:217], v[64:67]
	s_setprio 0
	s_barrier
	s_add_i32 s7, s68, s50
	v_lshl_add_u64 v[218:219], s[42:43], 0, v[130:131]
	s_mov_b32 m0, s7
	ds_read_b128 v[184:187], v163 offset:16384
	ds_read_b128 v[188:191], v163 offset:17408
	ds_read_b128 v[194:197], v163 offset:18432
	ds_read_b128 v[198:201], v163 offset:19456
	ds_read_b128 v[202:205], v163 offset:20480
	ds_read_b128 v[206:209], v163 offset:21504
	ds_read_b128 v[210:213], v163 offset:22528
	ds_read_b128 v[214:217], v163 offset:23552
	global_load_lds_dwordx4 v[218:219], off
	s_add_i32 m0, s7, 0x2000
	s_add_u32 s34, s42, 0x40000
	v_lshl_add_u64 v[220:221], s[42:43], 0, v[134:135]
	s_addc_u32 s35, s43, 0
	s_add_i32 s7, s69, s50
	global_load_lds_dwordx4 v[220:221], off
	v_lshl_add_u64 v[222:223], s[34:35], 0, v[130:131]
	s_mov_b32 m0, s7
	v_lshl_add_u64 v[224:225], s[44:45], 0, v[132:133]
	global_load_lds_dwordx4 v[222:223], off
	v_lshl_add_u64 v[222:223], s[34:35], 0, v[134:135]
	s_add_i32 m0, s7, 0x2000
	s_nop 0
	global_load_lds_dwordx4 v[222:223], off
	v_lshl_add_u64 v[222:223], s[44:45], 0, v[128:129]
	s_mov_b32 m0, s51
	s_nop 0
	global_load_lds_dwordx4 v[222:223], off
	s_mov_b32 m0, s58
	s_nop 0
	global_load_lds_dwordx4 v[224:225], off
	s_waitcnt vmcnt(8)
	s_waitcnt lgkmcnt(0)
	s_barrier
	s_setprio 1
	s_waitcnt lgkmcnt(0)
	v_mfma_f32_16x16x32_bf16 v[60:63], v[146:149], v[184:187], v[60:63]
	v_mfma_f32_16x16x32_bf16 v[56:59], v[154:157], v[184:187], v[56:59]
	v_mfma_f32_16x16x32_bf16 v[44:47], v[146:149], v[194:197], v[44:47]
	v_mfma_f32_16x16x32_bf16 v[40:43], v[154:157], v[194:197], v[40:43]
	v_mfma_f32_16x16x32_bf16 v[28:31], v[146:149], v[202:205], v[28:31]
	v_mfma_f32_16x16x32_bf16 v[24:27], v[154:157], v[202:205], v[24:27]
	v_mfma_f32_16x16x32_bf16 v[12:15], v[146:149], v[210:213], v[12:15]
	v_mfma_f32_16x16x32_bf16 v[8:11], v[154:157], v[210:213], v[8:11]
	v_mfma_f32_16x16x32_bf16 v[60:63], v[150:153], v[188:191], v[60:63]
	v_mfma_f32_16x16x32_bf16 v[56:59], v[164:167], v[188:191], v[56:59]
	v_mfma_f32_16x16x32_bf16 v[44:47], v[150:153], v[198:201], v[44:47]
	v_mfma_f32_16x16x32_bf16 v[40:43], v[164:167], v[198:201], v[40:43]
	v_mfma_f32_16x16x32_bf16 v[28:31], v[150:153], v[206:209], v[28:31]
	v_mfma_f32_16x16x32_bf16 v[24:27], v[164:167], v[206:209], v[24:27]
	v_mfma_f32_16x16x32_bf16 v[12:15], v[150:153], v[214:217], v[12:15]
	v_mfma_f32_16x16x32_bf16 v[8:11], v[164:167], v[214:217], v[8:11]
	v_mfma_f32_16x16x32_bf16 v[52:55], v[168:171], v[184:187], v[52:55]
	v_mfma_f32_16x16x32_bf16 v[48:51], v[176:179], v[184:187], v[48:51]
	v_mfma_f32_16x16x32_bf16 v[36:39], v[168:171], v[194:197], v[36:39]
	v_mfma_f32_16x16x32_bf16 v[32:35], v[176:179], v[194:197], v[32:35]
	v_mfma_f32_16x16x32_bf16 v[20:23], v[168:171], v[202:205], v[20:23]
	v_mfma_f32_16x16x32_bf16 v[16:19], v[176:179], v[202:205], v[16:19]
	v_mfma_f32_16x16x32_bf16 v[4:7], v[168:171], v[210:213], v[4:7]
	v_mfma_f32_16x16x32_bf16 v[0:3], v[176:179], v[210:213], v[0:3]
	v_mfma_f32_16x16x32_bf16 v[52:55], v[172:175], v[188:191], v[52:55]
	v_mfma_f32_16x16x32_bf16 v[48:51], v[180:183], v[188:191], v[48:51]
	v_mfma_f32_16x16x32_bf16 v[36:39], v[172:175], v[198:201], v[36:39]
	v_mfma_f32_16x16x32_bf16 v[32:35], v[180:183], v[198:201], v[32:35]
	v_mfma_f32_16x16x32_bf16 v[20:23], v[172:175], v[206:209], v[20:23]
	v_mfma_f32_16x16x32_bf16 v[16:19], v[180:183], v[206:209], v[16:19]
	v_mfma_f32_16x16x32_bf16 v[4:7], v[172:175], v[214:217], v[4:7]
	v_mfma_f32_16x16x32_bf16 v[0:3], v[180:183], v[214:217], v[0:3]
	s_setprio 0
	s_barrier
	s_add_i32 s7, 0, 0x18000
	v_add_u32_e32 v136, s7, v159
	s_add_i32 s9, 0, 0x1c000
	ds_read_b128 v[146:149], v136
	ds_read_b128 v[150:153], v136 offset:1024
	ds_read_b128 v[154:157], v136 offset:2048
	ds_read_b128 v[164:167], v136 offset:3072
	v_add_u32_e32 v136, s9, v159
	ds_read_b128 v[168:171], v136
	ds_read_b128 v[172:175], v136 offset:1024
	ds_read_b128 v[176:179], v136 offset:2048
	ds_read_b128 v[180:183], v136 offset:3072
	s_add_u32 s34, s44, 0x40000
	s_addc_u32 s35, s45, 0
	s_mov_b32 m0, s59
	v_lshl_add_u64 v[228:229], s[34:35], 0, v[128:129]
	ds_read_b128 v[184:187], v163 offset:32768
	ds_read_b128 v[188:191], v163 offset:33792
	ds_read_b128 v[194:197], v163 offset:34816
	ds_read_b128 v[198:201], v163 offset:35840
	ds_read_b128 v[202:205], v163 offset:36864
	ds_read_b128 v[206:209], v163 offset:37888
	ds_read_b128 v[210:213], v163 offset:38912
	ds_read_b128 v[214:217], v163 offset:39936
	global_load_lds_dwordx4 v[228:229], off
	v_lshl_add_u64 v[228:229], s[34:35], 0, v[132:133]
	s_mov_b32 m0, s60
	s_nop 0
	global_load_lds_dwordx4 v[228:229], off
	s_waitcnt vmcnt(8)
	s_waitcnt lgkmcnt(0)
	s_barrier
	s_setprio 1
	s_waitcnt lgkmcnt(0)
	v_mfma_f32_16x16x32_bf16 v[124:127], v[146:149], v[184:187], v[124:127]
	v_mfma_f32_16x16x32_bf16 v[120:123], v[154:157], v[184:187], v[120:123]
	v_mfma_f32_16x16x32_bf16 v[108:111], v[146:149], v[194:197], v[108:111]
	v_mfma_f32_16x16x32_bf16 v[104:107], v[154:157], v[194:197], v[104:107]
	v_mfma_f32_16x16x32_bf16 v[92:95], v[146:149], v[202:205], v[92:95]
	v_mfma_f32_16x16x32_bf16 v[88:91], v[154:157], v[202:205], v[88:91]
	v_mfma_f32_16x16x32_bf16 v[76:79], v[146:149], v[210:213], v[76:79]
	v_mfma_f32_16x16x32_bf16 v[72:75], v[154:157], v[210:213], v[72:75]
	v_mfma_f32_16x16x32_bf16 v[124:127], v[150:153], v[188:191], v[124:127]
	v_mfma_f32_16x16x32_bf16 v[120:123], v[164:167], v[188:191], v[120:123]
	v_mfma_f32_16x16x32_bf16 v[108:111], v[150:153], v[198:201], v[108:111]
	v_mfma_f32_16x16x32_bf16 v[104:107], v[164:167], v[198:201], v[104:107]
	v_mfma_f32_16x16x32_bf16 v[92:95], v[150:153], v[206:209], v[92:95]
	v_mfma_f32_16x16x32_bf16 v[88:91], v[164:167], v[206:209], v[88:91]
	v_mfma_f32_16x16x32_bf16 v[76:79], v[150:153], v[214:217], v[76:79]
	v_mfma_f32_16x16x32_bf16 v[72:75], v[164:167], v[214:217], v[72:75]
	v_mfma_f32_16x16x32_bf16 v[116:119], v[168:171], v[184:187], v[116:119]
	v_mfma_f32_16x16x32_bf16 v[112:115], v[176:179], v[184:187], v[112:115]
	v_mfma_f32_16x16x32_bf16 v[100:103], v[168:171], v[194:197], v[100:103]
	v_mfma_f32_16x16x32_bf16 v[96:99], v[176:179], v[194:197], v[96:99]
	v_mfma_f32_16x16x32_bf16 v[84:87], v[168:171], v[202:205], v[84:87]
	v_mfma_f32_16x16x32_bf16 v[80:83], v[176:179], v[202:205], v[80:83]
	v_mfma_f32_16x16x32_bf16 v[68:71], v[168:171], v[210:213], v[68:71]
	v_mfma_f32_16x16x32_bf16 v[64:67], v[176:179], v[210:213], v[64:67]
	v_mfma_f32_16x16x32_bf16 v[116:119], v[172:175], v[188:191], v[116:119]
	v_mfma_f32_16x16x32_bf16 v[112:115], v[180:183], v[188:191], v[112:115]
	v_mfma_f32_16x16x32_bf16 v[100:103], v[172:175], v[198:201], v[100:103]
	v_mfma_f32_16x16x32_bf16 v[96:99], v[180:183], v[198:201], v[96:99]
	v_mfma_f32_16x16x32_bf16 v[84:87], v[172:175], v[206:209], v[84:87]
	v_mfma_f32_16x16x32_bf16 v[80:83], v[180:183], v[206:209], v[80:83]
	v_mfma_f32_16x16x32_bf16 v[68:71], v[172:175], v[214:217], v[68:71]
	v_mfma_f32_16x16x32_bf16 v[64:67], v[180:183], v[214:217], v[64:67]
	s_setprio 0
	s_barrier
	s_add_i32 s7, s7, s50
	v_lshl_add_u64 v[218:219], v[218:219], 0, s[12:13]
	s_mov_b32 m0, s7
	ds_read_b128 v[184:187], v163 offset:49152
	ds_read_b128 v[188:191], v163 offset:50176
	ds_read_b128 v[194:197], v163 offset:51200
	ds_read_b128 v[198:201], v163 offset:52224
	ds_read_b128 v[202:205], v163 offset:53248
	ds_read_b128 v[206:209], v163 offset:54272
	ds_read_b128 v[210:213], v163 offset:55296
	ds_read_b128 v[214:217], v163 offset:56320
	global_load_lds_dwordx4 v[218:219], off
	s_add_i32 m0, s7, 0x2000
	s_add_u32 s34, s42, 0x40080
	v_lshl_add_u64 v[218:219], v[220:221], 0, s[12:13]
	s_addc_u32 s35, s43, 0
	s_add_i32 s7, s9, s50
	global_load_lds_dwordx4 v[218:219], off
	v_lshl_add_u64 v[218:219], s[34:35], 0, v[130:131]
	s_mov_b32 m0, s7
	s_nop 0
	global_load_lds_dwordx4 v[218:219], off
	v_lshl_add_u64 v[218:219], s[34:35], 0, v[134:135]
	s_add_i32 m0, s7, 0x2000
	s_nop 0
	global_load_lds_dwordx4 v[218:219], off
	v_lshl_add_u64 v[218:219], v[222:223], 0, s[12:13]
	s_mov_b32 m0, s63
	s_nop 0
	global_load_lds_dwordx4 v[218:219], off
	v_lshl_add_u64 v[218:219], v[224:225], 0, s[12:13]
	s_mov_b32 m0, s64
	s_nop 0
	global_load_lds_dwordx4 v[218:219], off
	s_waitcnt vmcnt(8)
	s_waitcnt lgkmcnt(0)
	s_barrier
	s_setprio 1
	s_waitcnt lgkmcnt(0)
	v_mfma_f32_16x16x32_bf16 v[60:63], v[146:149], v[184:187], v[60:63]
	v_mfma_f32_16x16x32_bf16 v[56:59], v[154:157], v[184:187], v[56:59]
	v_mfma_f32_16x16x32_bf16 v[44:47], v[146:149], v[194:197], v[44:47]
	v_mfma_f32_16x16x32_bf16 v[40:43], v[154:157], v[194:197], v[40:43]
	v_mfma_f32_16x16x32_bf16 v[28:31], v[146:149], v[202:205], v[28:31]
	v_mfma_f32_16x16x32_bf16 v[24:27], v[154:157], v[202:205], v[24:27]
	v_mfma_f32_16x16x32_bf16 v[12:15], v[146:149], v[210:213], v[12:15]
	v_mfma_f32_16x16x32_bf16 v[8:11], v[154:157], v[210:213], v[8:11]
	v_mfma_f32_16x16x32_bf16 v[60:63], v[150:153], v[188:191], v[60:63]
	v_mfma_f32_16x16x32_bf16 v[56:59], v[164:167], v[188:191], v[56:59]
	v_mfma_f32_16x16x32_bf16 v[44:47], v[150:153], v[198:201], v[44:47]
	v_mfma_f32_16x16x32_bf16 v[40:43], v[164:167], v[198:201], v[40:43]
	v_mfma_f32_16x16x32_bf16 v[28:31], v[150:153], v[206:209], v[28:31]
	v_mfma_f32_16x16x32_bf16 v[24:27], v[164:167], v[206:209], v[24:27]
	v_mfma_f32_16x16x32_bf16 v[12:15], v[150:153], v[214:217], v[12:15]
	v_mfma_f32_16x16x32_bf16 v[8:11], v[164:167], v[214:217], v[8:11]
	v_mfma_f32_16x16x32_bf16 v[52:55], v[168:171], v[184:187], v[52:55]
	v_mfma_f32_16x16x32_bf16 v[48:51], v[176:179], v[184:187], v[48:51]
	v_mfma_f32_16x16x32_bf16 v[36:39], v[168:171], v[194:197], v[36:39]
	v_mfma_f32_16x16x32_bf16 v[32:35], v[176:179], v[194:197], v[32:35]
	v_mfma_f32_16x16x32_bf16 v[20:23], v[168:171], v[202:205], v[20:23]
	v_mfma_f32_16x16x32_bf16 v[16:19], v[176:179], v[202:205], v[16:19]
	v_mfma_f32_16x16x32_bf16 v[4:7], v[168:171], v[210:213], v[4:7]
	v_mfma_f32_16x16x32_bf16 v[0:3], v[176:179], v[210:213], v[0:3]
	v_mfma_f32_16x16x32_bf16 v[52:55], v[172:175], v[188:191], v[52:55]
	v_mfma_f32_16x16x32_bf16 v[48:51], v[180:183], v[188:191], v[48:51]
	v_mfma_f32_16x16x32_bf16 v[36:39], v[172:175], v[198:201], v[36:39]
	v_mfma_f32_16x16x32_bf16 v[32:35], v[180:183], v[198:201], v[32:35]
	v_mfma_f32_16x16x32_bf16 v[20:23], v[172:175], v[206:209], v[20:23]
	v_mfma_f32_16x16x32_bf16 v[16:19], v[180:183], v[206:209], v[16:19]
	v_mfma_f32_16x16x32_bf16 v[4:7], v[172:175], v[214:217], v[4:7]
	v_mfma_f32_16x16x32_bf16 v[0:3], v[180:183], v[214:217], v[0:3]
	s_setprio 0
	s_barrier
	s_add_i32 s5, s5, 2
	s_add_u32 s40, s40, 0x100
	s_addc_u32 s41, s41, 0
	s_add_u32 s2, s2, 0x100
	s_addc_u32 s3, s3, 0
	s_cmp_gt_u32 s5, 13
	s_cbranch_scc0 .LBB0_244
	s_and_b64 vcc, exec, s[14:15]
	s_cbranch_vccz .LBB0_247
	s_barrier

.LBB0_440:
	ds_read_b128 v[148:151], v143
	ds_read_b128 v[152:155], v143 offset:1024
	ds_read_b128 v[156:159], v143 offset:2048
	ds_read_b128 v[160:163], v143 offset:3072
	ds_read_b128 v[164:167], v144
	ds_read_b128 v[168:171], v144 offset:1024
	ds_read_b128 v[172:175], v144 offset:2048
	ds_read_b128 v[176:179], v144 offset:3072
	s_add_u32 s40, s38, 0x100
	s_addc_u32 s41, s39, 0
	s_cmp_eq_u32 s68, 4
	s_cselect_b32 s45, s15, s41
	s_cselect_b32 s44, s14, s40
	s_cselect_b32 s43, s17, s13
	s_cselect_b32 s42, s16, s9
	s_mov_b32 m0, s58
	v_lshl_add_u64 v[214:215], s[38:39], 0, v[138:139]
	ds_read_b128 v[180:183], v145
	ds_read_b128 v[184:187], v145 offset:1024
	ds_read_b128 v[188:191], v145 offset:2048
	ds_read_b128 v[194:197], v145 offset:3072
	ds_read_b128 v[198:201], v145 offset:4096
	ds_read_b128 v[202:205], v145 offset:5120
	ds_read_b128 v[206:209], v145 offset:6144
	ds_read_b128 v[210:213], v145 offset:7168
	global_load_lds_dwordx4 v[214:215], off
	v_lshl_add_u64 v[214:215], s[38:39], 0, v[140:141]
	s_mov_b32 m0, s59
	s_nop 0
	global_load_lds_dwordx4 v[214:215], off
	s_waitcnt vmcnt(8)
	s_waitcnt lgkmcnt(0)
	s_barrier
	s_setprio 1
	s_waitcnt lgkmcnt(0)
	v_mfma_f32_16x16x32_bf16 v[124:127], v[148:151], v[180:183], v[124:127]
	v_mfma_f32_16x16x32_bf16 v[120:123], v[156:159], v[180:183], v[120:123]
	v_mfma_f32_16x16x32_bf16 v[116:119], v[148:151], v[188:191], v[116:119]
	v_mfma_f32_16x16x32_bf16 v[112:115], v[156:159], v[188:191], v[112:115]
	v_mfma_f32_16x16x32_bf16 v[104:107], v[148:151], v[198:201], v[104:107]
	v_mfma_f32_16x16x32_bf16 v[96:99], v[156:159], v[198:201], v[96:99]
	v_mfma_f32_16x16x32_bf16 v[88:91], v[148:151], v[206:209], v[88:91]
	v_mfma_f32_16x16x32_bf16 v[80:83], v[156:159], v[206:209], v[80:83]
	v_mfma_f32_16x16x32_bf16 v[124:127], v[152:155], v[184:187], v[124:127]
	v_mfma_f32_16x16x32_bf16 v[120:123], v[160:163], v[184:187], v[120:123]
	v_mfma_f32_16x16x32_bf16 v[116:119], v[152:155], v[194:197], v[116:119]
	v_mfma_f32_16x16x32_bf16 v[112:115], v[160:163], v[194:197], v[112:115]
	v_mfma_f32_16x16x32_bf16 v[104:107], v[152:155], v[202:205], v[104:107]
	v_mfma_f32_16x16x32_bf16 v[96:99], v[160:163], v[202:205], v[96:99]
	v_mfma_f32_16x16x32_bf16 v[88:91], v[152:155], v[210:213], v[88:91]
	v_mfma_f32_16x16x32_bf16 v[80:83], v[160:163], v[210:213], v[80:83]
	v_mfma_f32_16x16x32_bf16 v[108:111], v[164:167], v[180:183], v[108:111]
	v_mfma_f32_16x16x32_bf16 v[100:103], v[172:175], v[180:183], v[100:103]
	v_mfma_f32_16x16x32_bf16 v[92:95], v[164:167], v[188:191], v[92:95]
	v_mfma_f32_16x16x32_bf16 v[84:87], v[172:175], v[188:191], v[84:87]
	v_mfma_f32_16x16x32_bf16 v[76:79], v[164:167], v[198:201], v[76:79]
	v_mfma_f32_16x16x32_bf16 v[72:75], v[172:175], v[198:201], v[72:75]
	v_mfma_f32_16x16x32_bf16 v[68:71], v[164:167], v[206:209], v[68:71]
	v_mfma_f32_16x16x32_bf16 v[64:67], v[172:175], v[206:209], v[64:67]
	v_mfma_f32_16x16x32_bf16 v[108:111], v[168:171], v[184:187], v[108:111]
	v_mfma_f32_16x16x32_bf16 v[100:103], v[176:179], v[184:187], v[100:103]
	v_mfma_f32_16x16x32_bf16 v[92:95], v[168:171], v[194:197], v[92:95]
	v_mfma_f32_16x16x32_bf16 v[84:87], v[176:179], v[194:197], v[84:87]
	v_mfma_f32_16x16x32_bf16 v[76:79], v[168:171], v[202:205], v[76:79]
	v_mfma_f32_16x16x32_bf16 v[72:75], v[176:179], v[202:205], v[72:75]
	v_mfma_f32_16x16x32_bf16 v[68:71], v[168:171], v[210:213], v[68:71]
	v_mfma_f32_16x16x32_bf16 v[64:67], v[176:179], v[210:213], v[64:67]
	s_setprio 0
	s_barrier
	s_mov_b32 m0, s60
	v_lshl_add_u64 v[214:215], s[42:43], 0, v[132:133]
	s_add_u32 s38, s42, 0x20000
	ds_read_b128 v[180:183], v145 offset:16384
	ds_read_b128 v[184:187], v145 offset:17408
	ds_read_b128 v[188:191], v145 offset:18432
	ds_read_b128 v[194:197], v145 offset:19456
	ds_read_b128 v[198:201], v145 offset:20480
	ds_read_b128 v[202:205], v145 offset:21504
	ds_read_b128 v[206:209], v145 offset:22528
	ds_read_b128 v[210:213], v145 offset:23552
	global_load_lds_dwordx4 v[214:215], off
	v_lshl_add_u64 v[216:217], s[42:43], 0, v[128:129]
	s_mov_b32 m0, s61
	s_addc_u32 s39, s43, 0
	global_load_lds_dwordx4 v[216:217], off
	v_lshl_add_u64 v[218:219], s[38:39], 0, v[132:133]
	s_mov_b32 m0, s62
	v_lshl_add_u64 v[220:221], s[44:45], 0, v[130:131]
	global_load_lds_dwordx4 v[218:219], off
	v_lshl_add_u64 v[218:219], s[38:39], 0, v[128:129]
	s_mov_b32 m0, s63
	s_nop 0
	global_load_lds_dwordx4 v[218:219], off
	v_lshl_add_u64 v[218:219], s[44:45], 0, v[134:135]
	s_mov_b32 m0, s7
	s_nop 0
	global_load_lds_dwordx4 v[218:219], off
	s_mov_b32 m0, s33
	s_nop 0
	global_load_lds_dwordx4 v[220:221], off
	s_waitcnt vmcnt(8)
	s_waitcnt lgkmcnt(0)
	s_barrier
	s_setprio 1
	s_waitcnt lgkmcnt(0)
	v_mfma_f32_16x16x32_bf16 v[60:63], v[148:151], v[180:183], v[60:63]
	v_mfma_f32_16x16x32_bf16 v[56:59], v[156:159], v[180:183], v[56:59]
	v_mfma_f32_16x16x32_bf16 v[52:55], v[148:151], v[188:191], v[52:55]
	v_mfma_f32_16x16x32_bf16 v[48:51], v[156:159], v[188:191], v[48:51]
	v_mfma_f32_16x16x32_bf16 v[40:43], v[148:151], v[198:201], v[40:43]
	v_mfma_f32_16x16x32_bf16 v[32:35], v[156:159], v[198:201], v[32:35]
	v_mfma_f32_16x16x32_bf16 v[24:27], v[148:151], v[206:209], v[24:27]
	v_mfma_f32_16x16x32_bf16 v[16:19], v[156:159], v[206:209], v[16:19]
	v_mfma_f32_16x16x32_bf16 v[60:63], v[152:155], v[184:187], v[60:63]
	v_mfma_f32_16x16x32_bf16 v[56:59], v[160:163], v[184:187], v[56:59]
	v_mfma_f32_16x16x32_bf16 v[52:55], v[152:155], v[194:197], v[52:55]
	v_mfma_f32_16x16x32_bf16 v[48:51], v[160:163], v[194:197], v[48:51]
	v_mfma_f32_16x16x32_bf16 v[40:43], v[152:155], v[202:205], v[40:43]
	v_mfma_f32_16x16x32_bf16 v[32:35], v[160:163], v[202:205], v[32:35]
	v_mfma_f32_16x16x32_bf16 v[24:27], v[152:155], v[210:213], v[24:27]
	v_mfma_f32_16x16x32_bf16 v[16:19], v[160:163], v[210:213], v[16:19]
	v_mfma_f32_16x16x32_bf16 v[44:47], v[164:167], v[180:183], v[44:47]
	v_mfma_f32_16x16x32_bf16 v[36:39], v[172:175], v[180:183], v[36:39]
	v_mfma_f32_16x16x32_bf16 v[28:31], v[164:167], v[188:191], v[28:31]
	v_mfma_f32_16x16x32_bf16 v[20:23], v[172:175], v[188:191], v[20:23]
	v_mfma_f32_16x16x32_bf16 v[12:15], v[164:167], v[198:201], v[12:15]
	v_mfma_f32_16x16x32_bf16 v[8:11], v[172:175], v[198:201], v[8:11]
	v_mfma_f32_16x16x32_bf16 v[4:7], v[164:167], v[206:209], v[4:7]
	v_mfma_f32_16x16x32_bf16 v[0:3], v[172:175], v[206:209], v[0:3]
	v_mfma_f32_16x16x32_bf16 v[44:47], v[168:171], v[184:187], v[44:47]
	v_mfma_f32_16x16x32_bf16 v[36:39], v[176:179], v[184:187], v[36:39]
	v_mfma_f32_16x16x32_bf16 v[28:31], v[168:171], v[194:197], v[28:31]
	v_mfma_f32_16x16x32_bf16 v[20:23], v[176:179], v[194:197], v[20:23]
	v_mfma_f32_16x16x32_bf16 v[12:15], v[168:171], v[202:205], v[12:15]
	v_mfma_f32_16x16x32_bf16 v[8:11], v[176:179], v[202:205], v[8:11]
	v_mfma_f32_16x16x32_bf16 v[4:7], v[168:171], v[210:213], v[4:7]
	v_mfma_f32_16x16x32_bf16 v[0:3], v[176:179], v[210:213], v[0:3]
	s_setprio 0
	s_barrier
	ds_read_b128 v[148:151], v146
	ds_read_b128 v[152:155], v146 offset:1024
	ds_read_b128 v[156:159], v146 offset:2048
	ds_read_b128 v[160:163], v146 offset:3072
	ds_read_b128 v[164:167], v147
	ds_read_b128 v[168:171], v147 offset:1024
	ds_read_b128 v[172:175], v147 offset:2048
	ds_read_b128 v[176:179], v147 offset:3072
	s_add_u32 s38, s44, 0x30000
	s_addc_u32 s39, s45, 0
	s_mov_b32 m0, s34
	v_lshl_add_u64 v[222:223], s[38:39], 0, v[134:135]
	ds_read_b128 v[180:183], v145 offset:32768
	ds_read_b128 v[184:187], v145 offset:33792
	ds_read_b128 v[188:191], v145 offset:34816
	ds_read_b128 v[194:197], v145 offset:35840
	ds_read_b128 v[198:201], v145 offset:36864
	ds_read_b128 v[202:205], v145 offset:37888
	ds_read_b128 v[206:209], v145 offset:38912
	ds_read_b128 v[210:213], v145 offset:39936
	global_load_lds_dwordx4 v[222:223], off
	v_lshl_add_u64 v[222:223], s[38:39], 0, v[130:131]
	s_mov_b32 m0, s35
	s_nop 0
	global_load_lds_dwordx4 v[222:223], off
	s_waitcnt vmcnt(8)
	s_waitcnt lgkmcnt(0)
	s_barrier
	s_setprio 1
	s_waitcnt lgkmcnt(0)
	v_mfma_f32_16x16x32_bf16 v[124:127], v[148:151], v[180:183], v[124:127]
	v_mfma_f32_16x16x32_bf16 v[120:123], v[156:159], v[180:183], v[120:123]
	v_mfma_f32_16x16x32_bf16 v[116:119], v[148:151], v[188:191], v[116:119]
	v_mfma_f32_16x16x32_bf16 v[112:115], v[156:159], v[188:191], v[112:115]
	v_mfma_f32_16x16x32_bf16 v[104:107], v[148:151], v[198:201], v[104:107]
	v_mfma_f32_16x16x32_bf16 v[96:99], v[156:159], v[198:201], v[96:99]
	v_mfma_f32_16x16x32_bf16 v[88:91], v[148:151], v[206:209], v[88:91]
	v_mfma_f32_16x16x32_bf16 v[80:83], v[156:159], v[206:209], v[80:83]
	v_mfma_f32_16x16x32_bf16 v[124:127], v[152:155], v[184:187], v[124:127]
	v_mfma_f32_16x16x32_bf16 v[120:123], v[160:163], v[184:187], v[120:123]
	v_mfma_f32_16x16x32_bf16 v[116:119], v[152:155], v[194:197], v[116:119]
	v_mfma_f32_16x16x32_bf16 v[112:115], v[160:163], v[194:197], v[112:115]
	v_mfma_f32_16x16x32_bf16 v[104:107], v[152:155], v[202:205], v[104:107]
	v_mfma_f32_16x16x32_bf16 v[96:99], v[160:163], v[202:205], v[96:99]
	v_mfma_f32_16x16x32_bf16 v[88:91], v[152:155], v[210:213], v[88:91]
	v_mfma_f32_16x16x32_bf16 v[80:83], v[160:163], v[210:213], v[80:83]
	v_mfma_f32_16x16x32_bf16 v[108:111], v[164:167], v[180:183], v[108:111]
	v_mfma_f32_16x16x32_bf16 v[100:103], v[172:175], v[180:183], v[100:103]
	v_mfma_f32_16x16x32_bf16 v[92:95], v[164:167], v[188:191], v[92:95]
	v_mfma_f32_16x16x32_bf16 v[84:87], v[172:175], v[188:191], v[84:87]
	v_mfma_f32_16x16x32_bf16 v[76:79], v[164:167], v[198:201], v[76:79]
	v_mfma_f32_16x16x32_bf16 v[72:75], v[172:175], v[198:201], v[72:75]
	v_mfma_f32_16x16x32_bf16 v[68:71], v[164:167], v[206:209], v[68:71]
	v_mfma_f32_16x16x32_bf16 v[64:67], v[172:175], v[206:209], v[64:67]
	v_mfma_f32_16x16x32_bf16 v[108:111], v[168:171], v[184:187], v[108:111]
	v_mfma_f32_16x16x32_bf16 v[100:103], v[176:179], v[184:187], v[100:103]
	v_mfma_f32_16x16x32_bf16 v[92:95], v[168:171], v[194:197], v[92:95]
	v_mfma_f32_16x16x32_bf16 v[84:87], v[176:179], v[194:197], v[84:87]
	v_mfma_f32_16x16x32_bf16 v[76:79], v[168:171], v[202:205], v[76:79]
	v_mfma_f32_16x16x32_bf16 v[72:75], v[176:179], v[202:205], v[72:75]
	v_mfma_f32_16x16x32_bf16 v[68:71], v[168:171], v[210:213], v[68:71]
	v_mfma_f32_16x16x32_bf16 v[64:67], v[176:179], v[210:213], v[64:67]
	s_setprio 0
	s_barrier
	s_mov_b32 m0, s64
	v_lshl_add_u64 v[214:215], v[214:215], 0, s[4:5]
	s_add_u32 s38, s42, 0x20080
	ds_read_b128 v[180:183], v145 offset:49152
	ds_read_b128 v[184:187], v145 offset:50176
	ds_read_b128 v[188:191], v145 offset:51200
	ds_read_b128 v[194:197], v145 offset:52224
	ds_read_b128 v[198:201], v145 offset:53248
	ds_read_b128 v[202:205], v145 offset:54272
	ds_read_b128 v[206:209], v145 offset:55296
	ds_read_b128 v[210:213], v145 offset:56320
	global_load_lds_dwordx4 v[214:215], off
	v_lshl_add_u64 v[214:215], v[216:217], 0, s[4:5]
	s_mov_b32 m0, s65
	s_addc_u32 s39, s43, 0
	global_load_lds_dwordx4 v[214:215], off
	v_lshl_add_u64 v[214:215], s[38:39], 0, v[132:133]
	s_mov_b32 m0, s66
	s_nop 0
	global_load_lds_dwordx4 v[214:215], off
	v_lshl_add_u64 v[214:215], s[38:39], 0, v[128:129]
	s_add_i32 m0, s66, 0x2000
	s_nop 0
	global_load_lds_dwordx4 v[214:215], off
	v_lshl_add_u64 v[214:215], v[218:219], 0, s[4:5]
	s_mov_b32 m0, s49
	s_nop 0
	global_load_lds_dwordx4 v[214:215], off
	v_lshl_add_u64 v[214:215], v[220:221], 0, s[4:5]
	s_mov_b32 m0, s50
	s_nop 0
	global_load_lds_dwordx4 v[214:215], off
	s_waitcnt vmcnt(8)
	s_waitcnt lgkmcnt(0)
	s_barrier
	s_setprio 1
	s_waitcnt lgkmcnt(0)
	v_mfma_f32_16x16x32_bf16 v[60:63], v[148:151], v[180:183], v[60:63]
	v_mfma_f32_16x16x32_bf16 v[56:59], v[156:159], v[180:183], v[56:59]
	v_mfma_f32_16x16x32_bf16 v[52:55], v[148:151], v[188:191], v[52:55]
	v_mfma_f32_16x16x32_bf16 v[48:51], v[156:159], v[188:191], v[48:51]
	v_mfma_f32_16x16x32_bf16 v[40:43], v[148:151], v[198:201], v[40:43]
	v_mfma_f32_16x16x32_bf16 v[32:35], v[156:159], v[198:201], v[32:35]
	v_mfma_f32_16x16x32_bf16 v[24:27], v[148:151], v[206:209], v[24:27]
	v_mfma_f32_16x16x32_bf16 v[16:19], v[156:159], v[206:209], v[16:19]
	v_mfma_f32_16x16x32_bf16 v[60:63], v[152:155], v[184:187], v[60:63]
	v_mfma_f32_16x16x32_bf16 v[56:59], v[160:163], v[184:187], v[56:59]
	v_mfma_f32_16x16x32_bf16 v[52:55], v[152:155], v[194:197], v[52:55]
	v_mfma_f32_16x16x32_bf16 v[48:51], v[160:163], v[194:197], v[48:51]
	v_mfma_f32_16x16x32_bf16 v[40:43], v[152:155], v[202:205], v[40:43]
	v_mfma_f32_16x16x32_bf16 v[32:35], v[160:163], v[202:205], v[32:35]
	v_mfma_f32_16x16x32_bf16 v[24:27], v[152:155], v[210:213], v[24:27]
	v_mfma_f32_16x16x32_bf16 v[16:19], v[160:163], v[210:213], v[16:19]
	v_mfma_f32_16x16x32_bf16 v[44:47], v[164:167], v[180:183], v[44:47]
	v_mfma_f32_16x16x32_bf16 v[36:39], v[172:175], v[180:183], v[36:39]
	v_mfma_f32_16x16x32_bf16 v[28:31], v[164:167], v[188:191], v[28:31]
	v_mfma_f32_16x16x32_bf16 v[20:23], v[172:175], v[188:191], v[20:23]
	v_mfma_f32_16x16x32_bf16 v[12:15], v[164:167], v[198:201], v[12:15]
	v_mfma_f32_16x16x32_bf16 v[8:11], v[172:175], v[198:201], v[8:11]
	v_mfma_f32_16x16x32_bf16 v[4:7], v[164:167], v[206:209], v[4:7]
	v_mfma_f32_16x16x32_bf16 v[0:3], v[172:175], v[206:209], v[0:3]
	v_mfma_f32_16x16x32_bf16 v[44:47], v[168:171], v[184:187], v[44:47]
	v_mfma_f32_16x16x32_bf16 v[36:39], v[176:179], v[184:187], v[36:39]
	v_mfma_f32_16x16x32_bf16 v[28:31], v[168:171], v[194:197], v[28:31]
	v_mfma_f32_16x16x32_bf16 v[20:23], v[176:179], v[194:197], v[20:23]
	v_mfma_f32_16x16x32_bf16 v[12:15], v[168:171], v[202:205], v[12:15]
	v_mfma_f32_16x16x32_bf16 v[8:11], v[176:179], v[202:205], v[8:11]
	v_mfma_f32_16x16x32_bf16 v[4:7], v[168:171], v[210:213], v[4:7]
	v_mfma_f32_16x16x32_bf16 v[0:3], v[176:179], v[210:213], v[0:3]
	s_setprio 0
	s_barrier
	s_add_i32 s68, s68, 2
	s_add_u32 s9, s9, 0x100
	s_addc_u32 s13, s13, 0
	s_cmp_gt_u32 s68, 5
	s_mov_b64 s[38:39], s[40:41]
	s_cbranch_scc0 .LBB0_440
	s_and_b64 vcc, exec, s[10:11]
	s_cbranch_vccz .LBB0_443
	s_barrier

.LBB0_650:
	ds_read_b128 v[148:151], v145
	ds_read_b128 v[152:155], v145 offset:1024
	ds_read_b128 v[156:159], v145 offset:2048
	ds_read_b128 v[160:163], v145 offset:3072
	ds_read_b128 v[164:167], v146
	ds_read_b128 v[168:171], v146 offset:1024
	ds_read_b128 v[172:175], v146 offset:2048
	ds_read_b128 v[176:179], v146 offset:3072
	s_add_u32 s60, s58, 0x100
	s_addc_u32 s61, s59, 0
	s_cmp_eq_u32 s33, 8
	s_cselect_b32 s65, s45, s61
	s_cselect_b32 s64, s44, s60
	s_cselect_b32 s63, s49, s7
	s_cselect_b32 s62, s48, s3
	s_mov_b32 m0, s77
	v_lshl_add_u64 v[214:215], s[58:59], 0, v[138:139]
	ds_read_b128 v[180:183], v147
	ds_read_b128 v[184:187], v147 offset:1024
	ds_read_b128 v[188:191], v147 offset:2048
	ds_read_b128 v[194:197], v147 offset:3072
	ds_read_b128 v[198:201], v147 offset:4096
	ds_read_b128 v[202:205], v147 offset:5120
	ds_read_b128 v[206:209], v147 offset:6144
	ds_read_b128 v[210:213], v147 offset:7168
	global_load_lds_dwordx4 v[214:215], off
	v_lshl_add_u64 v[214:215], s[58:59], 0, v[140:141]
	s_mov_b32 m0, s78
	s_nop 0
	global_load_lds_dwordx4 v[214:215], off
	s_waitcnt vmcnt(8)
	s_waitcnt lgkmcnt(0)
	s_barrier
	s_setprio 1
	s_waitcnt lgkmcnt(0)
	v_mfma_f32_16x16x32_bf16 v[124:127], v[148:151], v[180:183], v[124:127]
	v_mfma_f32_16x16x32_bf16 v[120:123], v[156:159], v[180:183], v[120:123]
	v_mfma_f32_16x16x32_bf16 v[108:111], v[148:151], v[188:191], v[108:111]
	v_mfma_f32_16x16x32_bf16 v[104:107], v[156:159], v[188:191], v[104:107]
	v_mfma_f32_16x16x32_bf16 v[92:95], v[148:151], v[198:201], v[92:95]
	v_mfma_f32_16x16x32_bf16 v[88:91], v[156:159], v[198:201], v[88:91]
	v_mfma_f32_16x16x32_bf16 v[76:79], v[148:151], v[206:209], v[76:79]
	v_mfma_f32_16x16x32_bf16 v[72:75], v[156:159], v[206:209], v[72:75]
	v_mfma_f32_16x16x32_bf16 v[124:127], v[152:155], v[184:187], v[124:127]
	v_mfma_f32_16x16x32_bf16 v[120:123], v[160:163], v[184:187], v[120:123]
	v_mfma_f32_16x16x32_bf16 v[108:111], v[152:155], v[194:197], v[108:111]
	v_mfma_f32_16x16x32_bf16 v[104:107], v[160:163], v[194:197], v[104:107]
	v_mfma_f32_16x16x32_bf16 v[92:95], v[152:155], v[202:205], v[92:95]
	v_mfma_f32_16x16x32_bf16 v[88:91], v[160:163], v[202:205], v[88:91]
	v_mfma_f32_16x16x32_bf16 v[76:79], v[152:155], v[210:213], v[76:79]
	v_mfma_f32_16x16x32_bf16 v[72:75], v[160:163], v[210:213], v[72:75]
	v_mfma_f32_16x16x32_bf16 v[116:119], v[164:167], v[180:183], v[116:119]
	v_mfma_f32_16x16x32_bf16 v[112:115], v[172:175], v[180:183], v[112:115]
	v_mfma_f32_16x16x32_bf16 v[100:103], v[164:167], v[188:191], v[100:103]
	v_mfma_f32_16x16x32_bf16 v[96:99], v[172:175], v[188:191], v[96:99]
	v_mfma_f32_16x16x32_bf16 v[84:87], v[164:167], v[198:201], v[84:87]
	v_mfma_f32_16x16x32_bf16 v[80:83], v[172:175], v[198:201], v[80:83]
	v_mfma_f32_16x16x32_bf16 v[68:71], v[164:167], v[206:209], v[68:71]
	v_mfma_f32_16x16x32_bf16 v[64:67], v[172:175], v[206:209], v[64:67]
	v_mfma_f32_16x16x32_bf16 v[116:119], v[168:171], v[184:187], v[116:119]
	v_mfma_f32_16x16x32_bf16 v[112:115], v[176:179], v[184:187], v[112:115]
	v_mfma_f32_16x16x32_bf16 v[100:103], v[168:171], v[194:197], v[100:103]
	v_mfma_f32_16x16x32_bf16 v[96:99], v[176:179], v[194:197], v[96:99]
	v_mfma_f32_16x16x32_bf16 v[84:87], v[168:171], v[202:205], v[84:87]
	v_mfma_f32_16x16x32_bf16 v[80:83], v[176:179], v[202:205], v[80:83]
	v_mfma_f32_16x16x32_bf16 v[68:71], v[168:171], v[210:213], v[68:71]
	v_mfma_f32_16x16x32_bf16 v[64:67], v[176:179], v[210:213], v[64:67]
	s_setprio 0
	s_barrier
	s_mov_b32 m0, s79
	v_lshl_add_u64 v[214:215], s[62:63], 0, v[132:133]
	s_add_u32 s34, s62, 0x30000
	ds_read_b128 v[180:183], v147 offset:16384
	ds_read_b128 v[184:187], v147 offset:17408
	ds_read_b128 v[188:191], v147 offset:18432
	ds_read_b128 v[194:197], v147 offset:19456
	ds_read_b128 v[198:201], v147 offset:20480
	ds_read_b128 v[202:205], v147 offset:21504
	ds_read_b128 v[206:209], v147 offset:22528
	ds_read_b128 v[210:213], v147 offset:23552
	global_load_lds_dwordx4 v[214:215], off
	v_lshl_add_u64 v[216:217], s[62:63], 0, v[128:129]
	s_mov_b32 m0, s80
	s_addc_u32 s35, s63, 0
	s_add_i32 s43, s75, s68
	global_load_lds_dwordx4 v[216:217], off
	v_lshl_add_u64 v[218:219], s[34:35], 0, v[132:133]
	s_mov_b32 m0, s43
	v_lshl_add_u64 v[220:221], s[64:65], 0, v[130:131]
	global_load_lds_dwordx4 v[218:219], off
	v_lshl_add_u64 v[218:219], s[34:35], 0, v[128:129]
	s_add_i32 m0, s43, 0x2000
	s_nop 0
	global_load_lds_dwordx4 v[218:219], off
	v_lshl_add_u64 v[218:219], s[64:65], 0, v[134:135]
	s_mov_b32 m0, s57
	s_nop 0
	global_load_lds_dwordx4 v[218:219], off
	s_mov_b32 m0, s69
	s_nop 0
	global_load_lds_dwordx4 v[220:221], off
	s_waitcnt vmcnt(8)
	s_waitcnt lgkmcnt(0)
	s_barrier
	s_setprio 1
	s_waitcnt lgkmcnt(0)
	v_mfma_f32_16x16x32_bf16 v[60:63], v[148:151], v[180:183], v[60:63]
	v_mfma_f32_16x16x32_bf16 v[56:59], v[156:159], v[180:183], v[56:59]
	v_mfma_f32_16x16x32_bf16 v[44:47], v[148:151], v[188:191], v[44:47]
	v_mfma_f32_16x16x32_bf16 v[40:43], v[156:159], v[188:191], v[40:43]
	v_mfma_f32_16x16x32_bf16 v[28:31], v[148:151], v[198:201], v[28:31]
	v_mfma_f32_16x16x32_bf16 v[24:27], v[156:159], v[198:201], v[24:27]
	v_mfma_f32_16x16x32_bf16 v[12:15], v[148:151], v[206:209], v[12:15]
	v_mfma_f32_16x16x32_bf16 v[8:11], v[156:159], v[206:209], v[8:11]
	v_mfma_f32_16x16x32_bf16 v[60:63], v[152:155], v[184:187], v[60:63]
	v_mfma_f32_16x16x32_bf16 v[56:59], v[160:163], v[184:187], v[56:59]
	v_mfma_f32_16x16x32_bf16 v[44:47], v[152:155], v[194:197], v[44:47]
	v_mfma_f32_16x16x32_bf16 v[40:43], v[160:163], v[194:197], v[40:43]
	v_mfma_f32_16x16x32_bf16 v[28:31], v[152:155], v[202:205], v[28:31]
	v_mfma_f32_16x16x32_bf16 v[24:27], v[160:163], v[202:205], v[24:27]
	v_mfma_f32_16x16x32_bf16 v[12:15], v[152:155], v[210:213], v[12:15]
	v_mfma_f32_16x16x32_bf16 v[8:11], v[160:163], v[210:213], v[8:11]
	v_mfma_f32_16x16x32_bf16 v[52:55], v[164:167], v[180:183], v[52:55]
	v_mfma_f32_16x16x32_bf16 v[48:51], v[172:175], v[180:183], v[48:51]
	v_mfma_f32_16x16x32_bf16 v[36:39], v[164:167], v[188:191], v[36:39]
	v_mfma_f32_16x16x32_bf16 v[32:35], v[172:175], v[188:191], v[32:35]
	v_mfma_f32_16x16x32_bf16 v[20:23], v[164:167], v[198:201], v[20:23]
	v_mfma_f32_16x16x32_bf16 v[16:19], v[172:175], v[198:201], v[16:19]
	v_mfma_f32_16x16x32_bf16 v[4:7], v[164:167], v[206:209], v[4:7]
	v_mfma_f32_16x16x32_bf16 v[0:3], v[172:175], v[206:209], v[0:3]
	v_mfma_f32_16x16x32_bf16 v[52:55], v[168:171], v[184:187], v[52:55]
	v_mfma_f32_16x16x32_bf16 v[48:51], v[176:179], v[184:187], v[48:51]
	v_mfma_f32_16x16x32_bf16 v[36:39], v[168:171], v[194:197], v[36:39]
	v_mfma_f32_16x16x32_bf16 v[32:35], v[176:179], v[194:197], v[32:35]
	v_mfma_f32_16x16x32_bf16 v[20:23], v[168:171], v[202:205], v[20:23]
	v_mfma_f32_16x16x32_bf16 v[16:19], v[176:179], v[202:205], v[16:19]
	v_mfma_f32_16x16x32_bf16 v[4:7], v[168:171], v[210:213], v[4:7]
	v_mfma_f32_16x16x32_bf16 v[0:3], v[176:179], v[210:213], v[0:3]
	s_setprio 0
	s_barrier
	s_add_i32 s43, 0, 0x18000
	v_add_u32_e32 v136, s43, v143
	s_add_i32 s55, 0, 0x1c000
	ds_read_b128 v[148:151], v136
	ds_read_b128 v[152:155], v136 offset:1024
	ds_read_b128 v[156:159], v136 offset:2048
	ds_read_b128 v[160:163], v136 offset:3072
	v_add_u32_e32 v136, s55, v143
	ds_read_b128 v[164:167], v136
	ds_read_b128 v[168:171], v136 offset:1024
	ds_read_b128 v[172:175], v136 offset:2048
	ds_read_b128 v[176:179], v136 offset:3072
	s_add_u32 s34, s64, 0x30000
	s_addc_u32 s35, s65, 0
	s_mov_b32 m0, s70
	v_lshl_add_u64 v[222:223], s[34:35], 0, v[134:135]
	ds_read_b128 v[180:183], v147 offset:32768
	ds_read_b128 v[184:187], v147 offset:33792
	ds_read_b128 v[188:191], v147 offset:34816
	ds_read_b128 v[194:197], v147 offset:35840
	ds_read_b128 v[198:201], v147 offset:36864
	ds_read_b128 v[202:205], v147 offset:37888
	ds_read_b128 v[206:209], v147 offset:38912
	ds_read_b128 v[210:213], v147 offset:39936
	global_load_lds_dwordx4 v[222:223], off
	v_lshl_add_u64 v[222:223], s[34:35], 0, v[130:131]
	s_mov_b32 m0, s71
	s_nop 0
	global_load_lds_dwordx4 v[222:223], off
	s_waitcnt vmcnt(8)
	s_waitcnt lgkmcnt(0)
	s_barrier
	s_setprio 1
	s_waitcnt lgkmcnt(0)
	v_mfma_f32_16x16x32_bf16 v[124:127], v[148:151], v[180:183], v[124:127]
	v_mfma_f32_16x16x32_bf16 v[120:123], v[156:159], v[180:183], v[120:123]
	v_mfma_f32_16x16x32_bf16 v[108:111], v[148:151], v[188:191], v[108:111]
	v_mfma_f32_16x16x32_bf16 v[104:107], v[156:159], v[188:191], v[104:107]
	v_mfma_f32_16x16x32_bf16 v[92:95], v[148:151], v[198:201], v[92:95]
	v_mfma_f32_16x16x32_bf16 v[88:91], v[156:159], v[198:201], v[88:91]
	v_mfma_f32_16x16x32_bf16 v[76:79], v[148:151], v[206:209], v[76:79]
	v_mfma_f32_16x16x32_bf16 v[72:75], v[156:159], v[206:209], v[72:75]
	v_mfma_f32_16x16x32_bf16 v[124:127], v[152:155], v[184:187], v[124:127]
	v_mfma_f32_16x16x32_bf16 v[120:123], v[160:163], v[184:187], v[120:123]
	v_mfma_f32_16x16x32_bf16 v[108:111], v[152:155], v[194:197], v[108:111]
	v_mfma_f32_16x16x32_bf16 v[104:107], v[160:163], v[194:197], v[104:107]
	v_mfma_f32_16x16x32_bf16 v[92:95], v[152:155], v[202:205], v[92:95]
	v_mfma_f32_16x16x32_bf16 v[88:91], v[160:163], v[202:205], v[88:91]
	v_mfma_f32_16x16x32_bf16 v[76:79], v[152:155], v[210:213], v[76:79]
	v_mfma_f32_16x16x32_bf16 v[72:75], v[160:163], v[210:213], v[72:75]
	v_mfma_f32_16x16x32_bf16 v[116:119], v[164:167], v[180:183], v[116:119]
	v_mfma_f32_16x16x32_bf16 v[112:115], v[172:175], v[180:183], v[112:115]
	v_mfma_f32_16x16x32_bf16 v[100:103], v[164:167], v[188:191], v[100:103]
	v_mfma_f32_16x16x32_bf16 v[96:99], v[172:175], v[188:191], v[96:99]
	v_mfma_f32_16x16x32_bf16 v[84:87], v[164:167], v[198:201], v[84:87]
	v_mfma_f32_16x16x32_bf16 v[80:83], v[172:175], v[198:201], v[80:83]
	v_mfma_f32_16x16x32_bf16 v[68:71], v[164:167], v[206:209], v[68:71]
	v_mfma_f32_16x16x32_bf16 v[64:67], v[172:175], v[206:209], v[64:67]
	v_mfma_f32_16x16x32_bf16 v[116:119], v[168:171], v[184:187], v[116:119]
	v_mfma_f32_16x16x32_bf16 v[112:115], v[176:179], v[184:187], v[112:115]
	v_mfma_f32_16x16x32_bf16 v[100:103], v[168:171], v[194:197], v[100:103]
	v_mfma_f32_16x16x32_bf16 v[96:99], v[176:179], v[194:197], v[96:99]
	v_mfma_f32_16x16x32_bf16 v[84:87], v[168:171], v[202:205], v[84:87]
	v_mfma_f32_16x16x32_bf16 v[80:83], v[176:179], v[202:205], v[80:83]
	v_mfma_f32_16x16x32_bf16 v[68:71], v[168:171], v[210:213], v[68:71]
	v_mfma_f32_16x16x32_bf16 v[64:67], v[176:179], v[210:213], v[64:67]
	s_setprio 0
	s_barrier
	s_add_i32 s34, s43, s68
	v_lshl_add_u64 v[214:215], v[214:215], 0, s[10:11]
	s_mov_b32 m0, s34
	ds_read_b128 v[180:183], v147 offset:49152
	ds_read_b128 v[184:187], v147 offset:50176
	ds_read_b128 v[188:191], v147 offset:51200
	ds_read_b128 v[194:197], v147 offset:52224
	ds_read_b128 v[198:201], v147 offset:53248
	ds_read_b128 v[202:205], v147 offset:54272
	ds_read_b128 v[206:209], v147 offset:55296
	ds_read_b128 v[210:213], v147 offset:56320
	global_load_lds_dwordx4 v[214:215], off
	s_add_i32 m0, s34, 0x2000
	s_add_u32 s34, s62, 0x30080
	v_lshl_add_u64 v[214:215], v[216:217], 0, s[10:11]
	s_addc_u32 s35, s63, 0
	s_add_i32 s43, s55, s68
	global_load_lds_dwordx4 v[214:215], off
	v_lshl_add_u64 v[214:215], s[34:35], 0, v[132:133]
	s_mov_b32 m0, s43
	s_nop 0
	global_load_lds_dwordx4 v[214:215], off
	v_lshl_add_u64 v[214:215], s[34:35], 0, v[128:129]
	s_add_i32 m0, s43, 0x2000
	s_nop 0
	global_load_lds_dwordx4 v[214:215], off
	v_lshl_add_u64 v[214:215], v[218:219], 0, s[10:11]
	s_mov_b32 m0, s73
	s_nop 0
	global_load_lds_dwordx4 v[214:215], off
	v_lshl_add_u64 v[214:215], v[220:221], 0, s[10:11]
	s_mov_b32 m0, s74
	s_nop 0
	global_load_lds_dwordx4 v[214:215], off
	s_waitcnt vmcnt(8)
	s_waitcnt lgkmcnt(0)
	s_barrier
	s_setprio 1
	s_waitcnt lgkmcnt(0)
	v_mfma_f32_16x16x32_bf16 v[60:63], v[148:151], v[180:183], v[60:63]
	v_mfma_f32_16x16x32_bf16 v[56:59], v[156:159], v[180:183], v[56:59]
	v_mfma_f32_16x16x32_bf16 v[44:47], v[148:151], v[188:191], v[44:47]
	v_mfma_f32_16x16x32_bf16 v[40:43], v[156:159], v[188:191], v[40:43]
	v_mfma_f32_16x16x32_bf16 v[28:31], v[148:151], v[198:201], v[28:31]
	v_mfma_f32_16x16x32_bf16 v[24:27], v[156:159], v[198:201], v[24:27]
	v_mfma_f32_16x16x32_bf16 v[12:15], v[148:151], v[206:209], v[12:15]
	v_mfma_f32_16x16x32_bf16 v[8:11], v[156:159], v[206:209], v[8:11]
	v_mfma_f32_16x16x32_bf16 v[60:63], v[152:155], v[184:187], v[60:63]
	v_mfma_f32_16x16x32_bf16 v[56:59], v[160:163], v[184:187], v[56:59]
	v_mfma_f32_16x16x32_bf16 v[44:47], v[152:155], v[194:197], v[44:47]
	v_mfma_f32_16x16x32_bf16 v[40:43], v[160:163], v[194:197], v[40:43]
	v_mfma_f32_16x16x32_bf16 v[28:31], v[152:155], v[202:205], v[28:31]
	v_mfma_f32_16x16x32_bf16 v[24:27], v[160:163], v[202:205], v[24:27]
	v_mfma_f32_16x16x32_bf16 v[12:15], v[152:155], v[210:213], v[12:15]
	v_mfma_f32_16x16x32_bf16 v[8:11], v[160:163], v[210:213], v[8:11]
	v_mfma_f32_16x16x32_bf16 v[52:55], v[164:167], v[180:183], v[52:55]
	v_mfma_f32_16x16x32_bf16 v[48:51], v[172:175], v[180:183], v[48:51]
	v_mfma_f32_16x16x32_bf16 v[36:39], v[164:167], v[188:191], v[36:39]
	v_mfma_f32_16x16x32_bf16 v[32:35], v[172:175], v[188:191], v[32:35]
	v_mfma_f32_16x16x32_bf16 v[20:23], v[164:167], v[198:201], v[20:23]
	v_mfma_f32_16x16x32_bf16 v[16:19], v[172:175], v[198:201], v[16:19]
	v_mfma_f32_16x16x32_bf16 v[4:7], v[164:167], v[206:209], v[4:7]
	v_mfma_f32_16x16x32_bf16 v[0:3], v[172:175], v[206:209], v[0:3]
	v_mfma_f32_16x16x32_bf16 v[52:55], v[168:171], v[184:187], v[52:55]
	v_mfma_f32_16x16x32_bf16 v[48:51], v[176:179], v[184:187], v[48:51]
	v_mfma_f32_16x16x32_bf16 v[36:39], v[168:171], v[194:197], v[36:39]
	v_mfma_f32_16x16x32_bf16 v[32:35], v[176:179], v[194:197], v[32:35]
	v_mfma_f32_16x16x32_bf16 v[20:23], v[168:171], v[202:205], v[20:23]
	v_mfma_f32_16x16x32_bf16 v[16:19], v[176:179], v[202:205], v[16:19]
	v_mfma_f32_16x16x32_bf16 v[4:7], v[168:171], v[210:213], v[4:7]
	v_mfma_f32_16x16x32_bf16 v[0:3], v[176:179], v[210:213], v[0:3]
	s_setprio 0
	s_barrier
	s_add_i32 s33, s33, 2
	s_add_u32 s3, s3, 0x100
	s_addc_u32 s7, s7, 0
	s_cmp_gt_u32 s33, 9
	s_mov_b64 s[58:59], s[60:61]
	s_cbranch_scc0 .LBB0_650
	s_and_b64 vcc, exec, s[30:31]
	s_cbranch_vccz .LBB0_653
	s_barrier

.LBB0_726:
	ds_read_b128 v[64:67], v195
	ds_read_b128 v[72:75], v195 offset:1024
	ds_read_b128 v[80:83], v195 offset:2048
	ds_read_b128 v[84:87], v195 offset:3072
	ds_read_b128 v[144:147], v196
	ds_read_b128 v[148:151], v196 offset:1024
	ds_read_b128 v[152:155], v196 offset:2048
	ds_read_b128 v[156:159], v196 offset:3072
	s_add_u32 s35, s58, 0xfffe0080
	s_addc_u32 s43, s59, -1
	s_cmp_eq_u32 s34, 4
	s_cselect_b32 s63, s49, s43
	s_cselect_b32 s62, s48, s35
	s_cselect_b32 s61, s51, s33
	s_cselect_b32 s60, s50, s7
	v_lshl_add_u64 v[188:189], s[58:59], 0, v[172:173]
	s_add_i32 m0, s55, 0xc000
	ds_read_b128 v[160:163], v197
	ds_read_b128 v[180:183], v197 offset:1024
	ds_read_b128 v[184:187], v197 offset:2048
	ds_read_b128 v[198:201], v197 offset:3072
	ds_read_b128 v[202:205], v197 offset:4096
	ds_read_b128 v[206:209], v197 offset:5120
	ds_read_b128 v[210:213], v197 offset:6144
	ds_read_b128 v[214:217], v197 offset:7168
	global_load_lds_dwordx4 v[188:189], off
	v_lshl_add_u64 v[188:189], s[58:59], 0, v[174:175]
	s_add_i32 m0, s55, 0xe000
	s_nop 0
	global_load_lds_dwordx4 v[188:189], off
	s_waitcnt vmcnt(8)
	s_waitcnt lgkmcnt(0)
	s_barrier
	s_setprio 1
	s_waitcnt lgkmcnt(0)
	v_mfma_f32_16x16x32_bf16 v[140:143], v[64:67], v[160:163], v[140:143]
	v_mfma_f32_16x16x32_bf16 v[136:139], v[80:83], v[160:163], v[136:139]
	v_mfma_f32_16x16x32_bf16 v[124:127], v[64:67], v[184:187], v[124:127]
	v_mfma_f32_16x16x32_bf16 v[120:123], v[80:83], v[184:187], v[120:123]
	v_mfma_f32_16x16x32_bf16 v[108:111], v[64:67], v[202:205], v[108:111]
	v_mfma_f32_16x16x32_bf16 v[104:107], v[80:83], v[202:205], v[104:107]
	v_mfma_f32_16x16x32_bf16 v[92:95], v[64:67], v[210:213], v[92:95]
	v_mfma_f32_16x16x32_bf16 v[88:91], v[80:83], v[210:213], v[88:91]
	v_mfma_f32_16x16x32_bf16 v[140:143], v[72:75], v[180:183], v[140:143]
	v_mfma_f32_16x16x32_bf16 v[136:139], v[84:87], v[180:183], v[136:139]
	v_mfma_f32_16x16x32_bf16 v[124:127], v[72:75], v[198:201], v[124:127]
	v_mfma_f32_16x16x32_bf16 v[120:123], v[84:87], v[198:201], v[120:123]
	v_mfma_f32_16x16x32_bf16 v[108:111], v[72:75], v[206:209], v[108:111]
	v_mfma_f32_16x16x32_bf16 v[104:107], v[84:87], v[206:209], v[104:107]
	v_mfma_f32_16x16x32_bf16 v[92:95], v[72:75], v[214:217], v[92:95]
	v_mfma_f32_16x16x32_bf16 v[88:91], v[84:87], v[214:217], v[88:91]
	v_mfma_f32_16x16x32_bf16 v[132:135], v[144:147], v[160:163], v[132:135]
	v_mfma_f32_16x16x32_bf16 v[128:131], v[152:155], v[160:163], v[128:131]
	v_mfma_f32_16x16x32_bf16 v[116:119], v[144:147], v[184:187], v[116:119]
	v_mfma_f32_16x16x32_bf16 v[112:115], v[152:155], v[184:187], v[112:115]
	v_mfma_f32_16x16x32_bf16 v[100:103], v[144:147], v[202:205], v[100:103]
	v_mfma_f32_16x16x32_bf16 v[96:99], v[152:155], v[202:205], v[96:99]
	v_mfma_f32_16x16x32_bf16 v[76:79], v[144:147], v[210:213], v[76:79]
	v_mfma_f32_16x16x32_bf16 v[68:71], v[152:155], v[210:213], v[68:71]
	v_mfma_f32_16x16x32_bf16 v[132:135], v[148:151], v[180:183], v[132:135]
	v_mfma_f32_16x16x32_bf16 v[128:131], v[156:159], v[180:183], v[128:131]
	v_mfma_f32_16x16x32_bf16 v[116:119], v[148:151], v[198:201], v[116:119]
	v_mfma_f32_16x16x32_bf16 v[112:115], v[156:159], v[198:201], v[112:115]
	v_mfma_f32_16x16x32_bf16 v[100:103], v[148:151], v[206:209], v[100:103]
	v_mfma_f32_16x16x32_bf16 v[96:99], v[156:159], v[206:209], v[96:99]
	v_mfma_f32_16x16x32_bf16 v[76:79], v[148:151], v[214:217], v[76:79]
	v_mfma_f32_16x16x32_bf16 v[68:71], v[156:159], v[214:217], v[68:71]
	s_setprio 0
	s_barrier
	s_add_i32 s35, s2, s65
	v_lshl_add_u64 v[188:189], s[60:61], 0, v[166:167]
	s_mov_b32 m0, s35
	ds_read_b128 v[160:163], v197 offset:16384
	ds_read_b128 v[180:183], v197 offset:17408
	ds_read_b128 v[184:187], v197 offset:18432
	ds_read_b128 v[198:201], v197 offset:19456
	ds_read_b128 v[202:205], v197 offset:20480
	ds_read_b128 v[206:209], v197 offset:21504
	ds_read_b128 v[210:213], v197 offset:22528
	ds_read_b128 v[214:217], v197 offset:23552
	global_load_lds_dwordx4 v[188:189], off
	s_add_i32 m0, s35, 0x2000
	s_add_u32 s74, s60, 0x20000
	v_lshl_add_u64 v[218:219], s[60:61], 0, v[170:171]
	s_addc_u32 s75, s61, 0
	s_add_i32 s35, s3, s65
	global_load_lds_dwordx4 v[218:219], off
	v_lshl_add_u64 v[220:221], s[74:75], 0, v[166:167]
	s_mov_b32 m0, s35
	v_lshl_add_u64 v[222:223], s[62:63], 0, v[168:169]
	global_load_lds_dwordx4 v[220:221], off
	v_lshl_add_u64 v[220:221], s[74:75], 0, v[170:171]
	s_add_i32 m0, s35, 0x2000
	s_nop 0
	global_load_lds_dwordx4 v[220:221], off
	v_lshl_add_u64 v[220:221], s[62:63], 0, v[164:165]
	s_mov_b32 m0, s55
	s_nop 0
	global_load_lds_dwordx4 v[220:221], off
	s_mov_b32 m0, s57
	s_nop 0
	global_load_lds_dwordx4 v[222:223], off
	s_waitcnt vmcnt(8)
	s_waitcnt lgkmcnt(0)
	s_barrier
	s_setprio 1
	s_waitcnt lgkmcnt(0)
	v_mfma_f32_16x16x32_bf16 v[60:63], v[64:67], v[160:163], v[60:63]
	v_mfma_f32_16x16x32_bf16 v[56:59], v[80:83], v[160:163], v[56:59]
	v_mfma_f32_16x16x32_bf16 v[44:47], v[64:67], v[184:187], v[44:47]
	v_mfma_f32_16x16x32_bf16 v[40:43], v[80:83], v[184:187], v[40:43]
	v_mfma_f32_16x16x32_bf16 v[28:31], v[64:67], v[202:205], v[28:31]
	v_mfma_f32_16x16x32_bf16 v[20:23], v[80:83], v[202:205], v[20:23]
	v_mfma_f32_16x16x32_bf16 v[8:11], v[64:67], v[210:213], v[8:11]
	v_mfma_f32_16x16x32_bf16 v[0:3], v[80:83], v[210:213], v[0:3]
	v_mfma_f32_16x16x32_bf16 v[60:63], v[72:75], v[180:183], v[60:63]
	v_mfma_f32_16x16x32_bf16 v[56:59], v[84:87], v[180:183], v[56:59]
	v_mfma_f32_16x16x32_bf16 v[44:47], v[72:75], v[198:201], v[44:47]
	v_mfma_f32_16x16x32_bf16 v[40:43], v[84:87], v[198:201], v[40:43]
	v_mfma_f32_16x16x32_bf16 v[28:31], v[72:75], v[206:209], v[28:31]
	v_mfma_f32_16x16x32_bf16 v[20:23], v[84:87], v[206:209], v[20:23]
	v_mfma_f32_16x16x32_bf16 v[8:11], v[72:75], v[214:217], v[8:11]
	v_mfma_f32_16x16x32_bf16 v[0:3], v[84:87], v[214:217], v[0:3]
	v_mfma_f32_16x16x32_bf16 v[52:55], v[144:147], v[160:163], v[52:55]
	v_mfma_f32_16x16x32_bf16 v[48:51], v[152:155], v[160:163], v[48:51]
	v_mfma_f32_16x16x32_bf16 v[36:39], v[144:147], v[184:187], v[36:39]
	v_mfma_f32_16x16x32_bf16 v[32:35], v[152:155], v[184:187], v[32:35]
	v_mfma_f32_16x16x32_bf16 v[24:27], v[144:147], v[202:205], v[24:27]
	v_mfma_f32_16x16x32_bf16 v[16:19], v[152:155], v[202:205], v[16:19]
	v_mfma_f32_16x16x32_bf16 v[12:15], v[144:147], v[210:213], v[12:15]
	v_mfma_f32_16x16x32_bf16 v[4:7], v[152:155], v[210:213], v[4:7]
	v_mfma_f32_16x16x32_bf16 v[52:55], v[148:151], v[180:183], v[52:55]
	v_mfma_f32_16x16x32_bf16 v[48:51], v[156:159], v[180:183], v[48:51]
	v_mfma_f32_16x16x32_bf16 v[36:39], v[148:151], v[198:201], v[36:39]
	v_mfma_f32_16x16x32_bf16 v[32:35], v[156:159], v[198:201], v[32:35]
	v_mfma_f32_16x16x32_bf16 v[24:27], v[148:151], v[206:209], v[24:27]
	v_mfma_f32_16x16x32_bf16 v[16:19], v[156:159], v[206:209], v[16:19]
	v_mfma_f32_16x16x32_bf16 v[12:15], v[148:151], v[214:217], v[12:15]
	v_mfma_f32_16x16x32_bf16 v[4:7], v[156:159], v[214:217], v[4:7]
	s_setprio 0
	s_barrier
	s_add_i32 s35, 0, 0x18000
	s_add_i32 s43, 0, 0x1c000
	v_add_u32_e32 v84, s35, v191
	v_add_u32_e32 v156, s43, v191
	ds_read_b128 v[64:67], v84
	ds_read_b128 v[72:75], v84 offset:1024
	ds_read_b128 v[80:83], v84 offset:2048
	ds_read_b128 v[84:87], v84 offset:3072
	ds_read_b128 v[144:147], v156
	ds_read_b128 v[148:151], v156 offset:1024
	ds_read_b128 v[152:155], v156 offset:2048
	ds_read_b128 v[156:159], v156 offset:3072
	s_add_u32 s62, s62, 0x20000
	s_addc_u32 s63, s63, 0
	s_mov_b32 m0, s66
	v_lshl_add_u64 v[224:225], s[62:63], 0, v[164:165]
	ds_read_b128 v[160:163], v197 offset:32768
	ds_read_b128 v[180:183], v197 offset:33792
	ds_read_b128 v[184:187], v197 offset:34816
	ds_read_b128 v[198:201], v197 offset:35840
	ds_read_b128 v[202:205], v197 offset:36864
	ds_read_b128 v[206:209], v197 offset:37888
	ds_read_b128 v[210:213], v197 offset:38912
	ds_read_b128 v[214:217], v197 offset:39936
	global_load_lds_dwordx4 v[224:225], off
	v_lshl_add_u64 v[224:225], s[62:63], 0, v[168:169]
	s_mov_b32 m0, s67
	s_nop 0
	global_load_lds_dwordx4 v[224:225], off
	s_waitcnt vmcnt(8)
	s_waitcnt lgkmcnt(0)
	s_barrier
	s_setprio 1
	s_waitcnt lgkmcnt(0)
	v_mfma_f32_16x16x32_bf16 v[140:143], v[64:67], v[160:163], v[140:143]
	v_mfma_f32_16x16x32_bf16 v[136:139], v[80:83], v[160:163], v[136:139]
	v_mfma_f32_16x16x32_bf16 v[124:127], v[64:67], v[184:187], v[124:127]
	v_mfma_f32_16x16x32_bf16 v[120:123], v[80:83], v[184:187], v[120:123]
	v_mfma_f32_16x16x32_bf16 v[108:111], v[64:67], v[202:205], v[108:111]
	v_mfma_f32_16x16x32_bf16 v[104:107], v[80:83], v[202:205], v[104:107]
	v_mfma_f32_16x16x32_bf16 v[92:95], v[64:67], v[210:213], v[92:95]
	v_mfma_f32_16x16x32_bf16 v[88:91], v[80:83], v[210:213], v[88:91]
	v_mfma_f32_16x16x32_bf16 v[140:143], v[72:75], v[180:183], v[140:143]
	v_mfma_f32_16x16x32_bf16 v[136:139], v[84:87], v[180:183], v[136:139]
	v_mfma_f32_16x16x32_bf16 v[124:127], v[72:75], v[198:201], v[124:127]
	v_mfma_f32_16x16x32_bf16 v[120:123], v[84:87], v[198:201], v[120:123]
	v_mfma_f32_16x16x32_bf16 v[108:111], v[72:75], v[206:209], v[108:111]
	v_mfma_f32_16x16x32_bf16 v[104:107], v[84:87], v[206:209], v[104:107]
	v_mfma_f32_16x16x32_bf16 v[92:95], v[72:75], v[214:217], v[92:95]
	v_mfma_f32_16x16x32_bf16 v[88:91], v[84:87], v[214:217], v[88:91]
	v_mfma_f32_16x16x32_bf16 v[132:135], v[144:147], v[160:163], v[132:135]
	v_mfma_f32_16x16x32_bf16 v[128:131], v[152:155], v[160:163], v[128:131]
	v_mfma_f32_16x16x32_bf16 v[116:119], v[144:147], v[184:187], v[116:119]
	v_mfma_f32_16x16x32_bf16 v[112:115], v[152:155], v[184:187], v[112:115]
	v_mfma_f32_16x16x32_bf16 v[100:103], v[144:147], v[202:205], v[100:103]
	v_mfma_f32_16x16x32_bf16 v[96:99], v[152:155], v[202:205], v[96:99]
	v_mfma_f32_16x16x32_bf16 v[76:79], v[144:147], v[210:213], v[76:79]
	v_mfma_f32_16x16x32_bf16 v[68:71], v[152:155], v[210:213], v[68:71]
	v_mfma_f32_16x16x32_bf16 v[132:135], v[148:151], v[180:183], v[132:135]
	v_mfma_f32_16x16x32_bf16 v[128:131], v[156:159], v[180:183], v[128:131]
	v_mfma_f32_16x16x32_bf16 v[116:119], v[148:151], v[198:201], v[116:119]
	v_mfma_f32_16x16x32_bf16 v[112:115], v[156:159], v[198:201], v[112:115]
	v_mfma_f32_16x16x32_bf16 v[100:103], v[148:151], v[206:209], v[100:103]
	v_mfma_f32_16x16x32_bf16 v[96:99], v[156:159], v[206:209], v[96:99]
	v_mfma_f32_16x16x32_bf16 v[76:79], v[148:151], v[214:217], v[76:79]
	v_mfma_f32_16x16x32_bf16 v[68:71], v[156:159], v[214:217], v[68:71]
	s_setprio 0
	s_barrier
	s_add_i32 s35, s35, s65
	v_lshl_add_u64 v[188:189], v[188:189], 0, s[10:11]
	s_mov_b32 m0, s35
	ds_read_b128 v[160:163], v197 offset:49152
	ds_read_b128 v[180:183], v197 offset:50176
	ds_read_b128 v[184:187], v197 offset:51200
	ds_read_b128 v[198:201], v197 offset:52224
	ds_read_b128 v[202:205], v197 offset:53248
	ds_read_b128 v[206:209], v197 offset:54272
	ds_read_b128 v[210:213], v197 offset:55296
	ds_read_b128 v[214:217], v197 offset:56320
	global_load_lds_dwordx4 v[188:189], off
	s_add_i32 m0, s35, 0x2000
	s_add_u32 s60, s60, 0x20080
	v_lshl_add_u64 v[188:189], v[218:219], 0, s[10:11]
	s_addc_u32 s61, s61, 0
	s_add_i32 s35, s43, s65
	global_load_lds_dwordx4 v[188:189], off
	v_lshl_add_u64 v[188:189], s[60:61], 0, v[166:167]
	s_mov_b32 m0, s35
	s_nop 0
	global_load_lds_dwordx4 v[188:189], off
	v_lshl_add_u64 v[188:189], s[60:61], 0, v[170:171]
	s_add_i32 m0, s35, 0x2000
	s_nop 0
	global_load_lds_dwordx4 v[188:189], off
	v_lshl_add_u64 v[188:189], v[220:221], 0, s[10:11]
	s_mov_b32 m0, s69
	s_nop 0
	global_load_lds_dwordx4 v[188:189], off
	v_lshl_add_u64 v[188:189], v[222:223], 0, s[10:11]
	s_mov_b32 m0, s70
	s_nop 0
	global_load_lds_dwordx4 v[188:189], off
	s_waitcnt vmcnt(8)
	s_waitcnt lgkmcnt(0)
	s_barrier
	s_setprio 1
	s_waitcnt lgkmcnt(0)
	v_mfma_f32_16x16x32_bf16 v[60:63], v[64:67], v[160:163], v[60:63]
	v_mfma_f32_16x16x32_bf16 v[56:59], v[80:83], v[160:163], v[56:59]
	v_mfma_f32_16x16x32_bf16 v[44:47], v[64:67], v[184:187], v[44:47]
	v_mfma_f32_16x16x32_bf16 v[40:43], v[80:83], v[184:187], v[40:43]
	v_mfma_f32_16x16x32_bf16 v[28:31], v[64:67], v[202:205], v[28:31]
	v_mfma_f32_16x16x32_bf16 v[20:23], v[80:83], v[202:205], v[20:23]
	v_mfma_f32_16x16x32_bf16 v[8:11], v[64:67], v[210:213], v[8:11]
	v_mfma_f32_16x16x32_bf16 v[0:3], v[80:83], v[210:213], v[0:3]
	v_mfma_f32_16x16x32_bf16 v[60:63], v[72:75], v[180:183], v[60:63]
	v_mfma_f32_16x16x32_bf16 v[56:59], v[84:87], v[180:183], v[56:59]
	v_mfma_f32_16x16x32_bf16 v[44:47], v[72:75], v[198:201], v[44:47]
	v_mfma_f32_16x16x32_bf16 v[40:43], v[84:87], v[198:201], v[40:43]
	v_mfma_f32_16x16x32_bf16 v[28:31], v[72:75], v[206:209], v[28:31]
	v_mfma_f32_16x16x32_bf16 v[20:23], v[84:87], v[206:209], v[20:23]
	v_mfma_f32_16x16x32_bf16 v[8:11], v[72:75], v[214:217], v[8:11]
	v_mfma_f32_16x16x32_bf16 v[0:3], v[84:87], v[214:217], v[0:3]
	v_mfma_f32_16x16x32_bf16 v[52:55], v[144:147], v[160:163], v[52:55]
	v_mfma_f32_16x16x32_bf16 v[48:51], v[152:155], v[160:163], v[48:51]
	v_mfma_f32_16x16x32_bf16 v[36:39], v[144:147], v[184:187], v[36:39]
	v_mfma_f32_16x16x32_bf16 v[32:35], v[152:155], v[184:187], v[32:35]
	v_mfma_f32_16x16x32_bf16 v[24:27], v[144:147], v[202:205], v[24:27]
	v_mfma_f32_16x16x32_bf16 v[16:19], v[152:155], v[202:205], v[16:19]
	v_mfma_f32_16x16x32_bf16 v[12:15], v[144:147], v[210:213], v[12:15]
	v_mfma_f32_16x16x32_bf16 v[4:7], v[152:155], v[210:213], v[4:7]
	v_mfma_f32_16x16x32_bf16 v[52:55], v[148:151], v[180:183], v[52:55]
	v_mfma_f32_16x16x32_bf16 v[48:51], v[156:159], v[180:183], v[48:51]
	v_mfma_f32_16x16x32_bf16 v[36:39], v[148:151], v[198:201], v[36:39]
	v_mfma_f32_16x16x32_bf16 v[32:35], v[156:159], v[198:201], v[32:35]
	v_mfma_f32_16x16x32_bf16 v[24:27], v[148:151], v[206:209], v[24:27]
	v_mfma_f32_16x16x32_bf16 v[16:19], v[156:159], v[206:209], v[16:19]
	v_mfma_f32_16x16x32_bf16 v[12:15], v[148:151], v[214:217], v[12:15]
	v_mfma_f32_16x16x32_bf16 v[4:7], v[156:159], v[214:217], v[4:7]
	s_setprio 0
	s_barrier
	s_add_i32 s34, s34, 2
	s_add_u32 s58, s58, 0x100
	s_addc_u32 s59, s59, 0
	s_add_u32 s7, s7, 0x100
	s_addc_u32 s33, s33, 0
	s_cmp_gt_u32 s34, 5
	s_cbranch_scc0 .LBB0_726
	s_and_b64 vcc, exec, s[30:31]
	s_cbranch_vccz .LBB0_729
	s_barrier

.LBB0_804:
	v_add_u32_e32 v140, s70, v228
	v_add_u32_e32 v156, s71, v228
	ds_read_b128 v[128:131], v140
	ds_read_b128 v[132:135], v140 offset:1024
	ds_read_b128 v[136:139], v140 offset:2048
	ds_read_b128 v[140:143], v140 offset:3072
	ds_read_b128 v[144:147], v156
	ds_read_b128 v[148:151], v156 offset:1024
	ds_read_b128 v[152:155], v156 offset:2048
	ds_read_b128 v[156:159], v156 offset:3072
	s_add_u32 s9, s54, 0xfffe0080
	s_addc_u32 s33, s55, -1
	s_cmp_eq_u32 s7, 4
	s_cselect_b32 s59, s51, s33
	s_cselect_b32 s58, s50, s9
	s_cselect_b32 s57, s53, s5
	s_cselect_b32 s56, s52, s3
	v_lshl_add_u64 v[210:211], s[54:55], 0, v[202:203]
	s_add_i32 m0, s61, 0xc000
	ds_read_b128 v[160:163], v230
	ds_read_b128 v[164:167], v230 offset:1024
	ds_read_b128 v[168:171], v230 offset:2048
	ds_read_b128 v[172:175], v230 offset:3072
	ds_read_b128 v[176:179], v230 offset:4096
	ds_read_b128 v[180:183], v230 offset:5120
	ds_read_b128 v[184:187], v230 offset:6144
	ds_read_b128 v[188:191], v230 offset:7168
	global_load_lds_dwordx4 v[210:211], off
	v_lshl_add_u64 v[210:211], s[54:55], 0, v[204:205]
	s_add_i32 m0, s61, 0xe000
	s_nop 0
	global_load_lds_dwordx4 v[210:211], off
	s_waitcnt vmcnt(8)
	s_waitcnt lgkmcnt(0)
	s_barrier
	s_setprio 1
	s_waitcnt lgkmcnt(0)
	v_mfma_f32_16x16x32_bf16 v[124:127], v[128:131], v[160:163], v[124:127]
	v_mfma_f32_16x16x32_bf16 v[120:123], v[136:139], v[160:163], v[120:123]
	v_mfma_f32_16x16x32_bf16 v[116:119], v[128:131], v[168:171], v[116:119]
	v_mfma_f32_16x16x32_bf16 v[112:115], v[136:139], v[168:171], v[112:115]
	v_mfma_f32_16x16x32_bf16 v[108:111], v[128:131], v[176:179], v[108:111]
	v_mfma_f32_16x16x32_bf16 v[104:107], v[136:139], v[176:179], v[104:107]
	v_mfma_f32_16x16x32_bf16 v[100:103], v[128:131], v[184:187], v[100:103]
	v_mfma_f32_16x16x32_bf16 v[96:99], v[136:139], v[184:187], v[96:99]
	v_mfma_f32_16x16x32_bf16 v[124:127], v[132:135], v[164:167], v[124:127]
	v_mfma_f32_16x16x32_bf16 v[120:123], v[140:143], v[164:167], v[120:123]
	v_mfma_f32_16x16x32_bf16 v[116:119], v[132:135], v[172:175], v[116:119]
	v_mfma_f32_16x16x32_bf16 v[112:115], v[140:143], v[172:175], v[112:115]
	v_mfma_f32_16x16x32_bf16 v[108:111], v[132:135], v[180:183], v[108:111]
	v_mfma_f32_16x16x32_bf16 v[104:107], v[140:143], v[180:183], v[104:107]
	v_mfma_f32_16x16x32_bf16 v[100:103], v[132:135], v[188:191], v[100:103]
	v_mfma_f32_16x16x32_bf16 v[96:99], v[140:143], v[188:191], v[96:99]
	v_mfma_f32_16x16x32_bf16 v[92:95], v[144:147], v[160:163], v[92:95]
	v_mfma_f32_16x16x32_bf16 v[88:91], v[152:155], v[160:163], v[88:91]
	v_mfma_f32_16x16x32_bf16 v[84:87], v[144:147], v[168:171], v[84:87]
	v_mfma_f32_16x16x32_bf16 v[80:83], v[152:155], v[168:171], v[80:83]
	v_mfma_f32_16x16x32_bf16 v[76:79], v[144:147], v[176:179], v[76:79]
	v_mfma_f32_16x16x32_bf16 v[72:75], v[152:155], v[176:179], v[72:75]
	v_mfma_f32_16x16x32_bf16 v[68:71], v[144:147], v[184:187], v[68:71]
	v_mfma_f32_16x16x32_bf16 v[64:67], v[152:155], v[184:187], v[64:67]
	v_mfma_f32_16x16x32_bf16 v[92:95], v[148:151], v[164:167], v[92:95]
	v_mfma_f32_16x16x32_bf16 v[88:91], v[156:159], v[164:167], v[88:91]
	v_mfma_f32_16x16x32_bf16 v[84:87], v[148:151], v[172:175], v[84:87]
	v_mfma_f32_16x16x32_bf16 v[80:83], v[156:159], v[172:175], v[80:83]
	v_mfma_f32_16x16x32_bf16 v[76:79], v[148:151], v[180:183], v[76:79]
	v_mfma_f32_16x16x32_bf16 v[72:75], v[156:159], v[180:183], v[72:75]
	v_mfma_f32_16x16x32_bf16 v[68:71], v[148:151], v[188:191], v[68:71]
	v_mfma_f32_16x16x32_bf16 v[64:67], v[156:159], v[188:191], v[64:67]
	s_setprio 0
	s_barrier
	s_add_i32 s9, s70, s60
	v_lshl_add_u64 v[210:211], s[56:57], 0, v[196:197]
	s_mov_b32 m0, s9
	ds_read_b128 v[160:163], v230 offset:16384
	ds_read_b128 v[164:167], v230 offset:17408
	ds_read_b128 v[168:171], v230 offset:18432
	ds_read_b128 v[172:175], v230 offset:19456
	ds_read_b128 v[176:179], v230 offset:20480
	ds_read_b128 v[180:183], v230 offset:21504
	ds_read_b128 v[184:187], v230 offset:22528
	ds_read_b128 v[188:191], v230 offset:23552
	global_load_lds_dwordx4 v[210:211], off
	s_add_i32 m0, s9, 0x2000
	s_add_u32 s34, s56, 0x20000
	v_lshl_add_u64 v[212:213], s[56:57], 0, v[200:201]
	s_addc_u32 s35, s57, 0
	s_add_i32 s9, s71, s60
	global_load_lds_dwordx4 v[212:213], off
	v_lshl_add_u64 v[214:215], s[34:35], 0, v[196:197]
	s_mov_b32 m0, s9
	v_lshl_add_u64 v[216:217], s[58:59], 0, v[198:199]
	global_load_lds_dwordx4 v[214:215], off
	v_lshl_add_u64 v[214:215], s[34:35], 0, v[200:201]
	s_add_i32 m0, s9, 0x2000
	s_nop 0
	global_load_lds_dwordx4 v[214:215], off
	v_lshl_add_u64 v[214:215], s[58:59], 0, v[194:195]
	s_mov_b32 m0, s61
	s_nop 0
	global_load_lds_dwordx4 v[214:215], off
	s_mov_b32 m0, s62
	s_nop 0
	global_load_lds_dwordx4 v[216:217], off
	s_waitcnt vmcnt(8)
	s_waitcnt lgkmcnt(0)
	s_barrier
	s_setprio 1
	s_waitcnt lgkmcnt(0)
	v_mfma_f32_16x16x32_bf16 v[60:63], v[128:131], v[160:163], v[60:63]
	v_mfma_f32_16x16x32_bf16 v[56:59], v[136:139], v[160:163], v[56:59]
	v_mfma_f32_16x16x32_bf16 v[52:55], v[128:131], v[168:171], v[52:55]
	v_mfma_f32_16x16x32_bf16 v[48:51], v[136:139], v[168:171], v[48:51]
	v_mfma_f32_16x16x32_bf16 v[44:47], v[128:131], v[176:179], v[44:47]
	v_mfma_f32_16x16x32_bf16 v[40:43], v[136:139], v[176:179], v[40:43]
	v_mfma_f32_16x16x32_bf16 v[36:39], v[128:131], v[184:187], v[36:39]
	v_mfma_f32_16x16x32_bf16 v[32:35], v[136:139], v[184:187], v[32:35]
	v_mfma_f32_16x16x32_bf16 v[60:63], v[132:135], v[164:167], v[60:63]
	v_mfma_f32_16x16x32_bf16 v[56:59], v[140:143], v[164:167], v[56:59]
	v_mfma_f32_16x16x32_bf16 v[52:55], v[132:135], v[172:175], v[52:55]
	v_mfma_f32_16x16x32_bf16 v[48:51], v[140:143], v[172:175], v[48:51]
	v_mfma_f32_16x16x32_bf16 v[44:47], v[132:135], v[180:183], v[44:47]
	v_mfma_f32_16x16x32_bf16 v[40:43], v[140:143], v[180:183], v[40:43]
	v_mfma_f32_16x16x32_bf16 v[36:39], v[132:135], v[188:191], v[36:39]
	v_mfma_f32_16x16x32_bf16 v[32:35], v[140:143], v[188:191], v[32:35]
	v_mfma_f32_16x16x32_bf16 v[28:31], v[144:147], v[160:163], v[28:31]
	v_mfma_f32_16x16x32_bf16 v[24:27], v[152:155], v[160:163], v[24:27]
	v_mfma_f32_16x16x32_bf16 v[20:23], v[144:147], v[168:171], v[20:23]
	v_mfma_f32_16x16x32_bf16 v[16:19], v[152:155], v[168:171], v[16:19]
	v_mfma_f32_16x16x32_bf16 v[12:15], v[144:147], v[176:179], v[12:15]
	v_mfma_f32_16x16x32_bf16 v[8:11], v[152:155], v[176:179], v[8:11]
	v_mfma_f32_16x16x32_bf16 v[4:7], v[144:147], v[184:187], v[4:7]
	v_mfma_f32_16x16x32_bf16 v[0:3], v[152:155], v[184:187], v[0:3]
	v_mfma_f32_16x16x32_bf16 v[28:31], v[148:151], v[164:167], v[28:31]
	v_mfma_f32_16x16x32_bf16 v[24:27], v[156:159], v[164:167], v[24:27]
	v_mfma_f32_16x16x32_bf16 v[20:23], v[148:151], v[172:175], v[20:23]
	v_mfma_f32_16x16x32_bf16 v[16:19], v[156:159], v[172:175], v[16:19]
	v_mfma_f32_16x16x32_bf16 v[12:15], v[148:151], v[180:183], v[12:15]
	v_mfma_f32_16x16x32_bf16 v[8:11], v[156:159], v[180:183], v[8:11]
	v_mfma_f32_16x16x32_bf16 v[4:7], v[148:151], v[188:191], v[4:7]
	v_mfma_f32_16x16x32_bf16 v[0:3], v[156:159], v[188:191], v[0:3]
	s_setprio 0
	s_barrier
	s_add_i32 s9, 0, 0x18000
	s_add_i32 s33, 0, 0x1c000
	v_add_u32_e32 v140, s9, v228
	v_add_u32_e32 v156, s33, v228
	ds_read_b128 v[128:131], v140
	ds_read_b128 v[132:135], v140 offset:1024
	ds_read_b128 v[136:139], v140 offset:2048
	ds_read_b128 v[140:143], v140 offset:3072
	ds_read_b128 v[144:147], v156
	ds_read_b128 v[148:151], v156 offset:1024
	ds_read_b128 v[152:155], v156 offset:2048
	ds_read_b128 v[156:159], v156 offset:3072
	s_add_u32 s34, s58, 0x20000
	s_addc_u32 s35, s59, 0
	s_mov_b32 m0, s63
	v_lshl_add_u64 v[218:219], s[34:35], 0, v[194:195]
	ds_read_b128 v[160:163], v230 offset:32768
	ds_read_b128 v[164:167], v230 offset:33792
	ds_read_b128 v[168:171], v230 offset:34816
	ds_read_b128 v[172:175], v230 offset:35840
	ds_read_b128 v[176:179], v230 offset:36864
	ds_read_b128 v[180:183], v230 offset:37888
	ds_read_b128 v[184:187], v230 offset:38912
	ds_read_b128 v[188:191], v230 offset:39936
	global_load_lds_dwordx4 v[218:219], off
	v_lshl_add_u64 v[218:219], s[34:35], 0, v[198:199]
	s_mov_b32 m0, s64
	s_nop 0
	global_load_lds_dwordx4 v[218:219], off
	s_waitcnt vmcnt(8)
	s_waitcnt lgkmcnt(0)
	s_barrier
	s_setprio 1
	s_waitcnt lgkmcnt(0)
	v_mfma_f32_16x16x32_bf16 v[124:127], v[128:131], v[160:163], v[124:127]
	v_mfma_f32_16x16x32_bf16 v[120:123], v[136:139], v[160:163], v[120:123]
	v_mfma_f32_16x16x32_bf16 v[116:119], v[128:131], v[168:171], v[116:119]
	v_mfma_f32_16x16x32_bf16 v[112:115], v[136:139], v[168:171], v[112:115]
	v_mfma_f32_16x16x32_bf16 v[108:111], v[128:131], v[176:179], v[108:111]
	v_mfma_f32_16x16x32_bf16 v[104:107], v[136:139], v[176:179], v[104:107]
	v_mfma_f32_16x16x32_bf16 v[100:103], v[128:131], v[184:187], v[100:103]
	v_mfma_f32_16x16x32_bf16 v[96:99], v[136:139], v[184:187], v[96:99]
	v_mfma_f32_16x16x32_bf16 v[124:127], v[132:135], v[164:167], v[124:127]
	v_mfma_f32_16x16x32_bf16 v[120:123], v[140:143], v[164:167], v[120:123]
	v_mfma_f32_16x16x32_bf16 v[116:119], v[132:135], v[172:175], v[116:119]
	v_mfma_f32_16x16x32_bf16 v[112:115], v[140:143], v[172:175], v[112:115]
	v_mfma_f32_16x16x32_bf16 v[108:111], v[132:135], v[180:183], v[108:111]
	v_mfma_f32_16x16x32_bf16 v[104:107], v[140:143], v[180:183], v[104:107]
	v_mfma_f32_16x16x32_bf16 v[100:103], v[132:135], v[188:191], v[100:103]
	v_mfma_f32_16x16x32_bf16 v[96:99], v[140:143], v[188:191], v[96:99]
	v_mfma_f32_16x16x32_bf16 v[92:95], v[144:147], v[160:163], v[92:95]
	v_mfma_f32_16x16x32_bf16 v[88:91], v[152:155], v[160:163], v[88:91]
	v_mfma_f32_16x16x32_bf16 v[84:87], v[144:147], v[168:171], v[84:87]
	v_mfma_f32_16x16x32_bf16 v[80:83], v[152:155], v[168:171], v[80:83]
	v_mfma_f32_16x16x32_bf16 v[76:79], v[144:147], v[176:179], v[76:79]
	v_mfma_f32_16x16x32_bf16 v[72:75], v[152:155], v[176:179], v[72:75]
	v_mfma_f32_16x16x32_bf16 v[68:71], v[144:147], v[184:187], v[68:71]
	v_mfma_f32_16x16x32_bf16 v[64:67], v[152:155], v[184:187], v[64:67]
	v_mfma_f32_16x16x32_bf16 v[92:95], v[148:151], v[164:167], v[92:95]
	v_mfma_f32_16x16x32_bf16 v[88:91], v[156:159], v[164:167], v[88:91]
	v_mfma_f32_16x16x32_bf16 v[84:87], v[148:151], v[172:175], v[84:87]
	v_mfma_f32_16x16x32_bf16 v[80:83], v[156:159], v[172:175], v[80:83]
	v_mfma_f32_16x16x32_bf16 v[76:79], v[148:151], v[180:183], v[76:79]
	v_mfma_f32_16x16x32_bf16 v[72:75], v[156:159], v[180:183], v[72:75]
	v_mfma_f32_16x16x32_bf16 v[68:71], v[148:151], v[188:191], v[68:71]
	v_mfma_f32_16x16x32_bf16 v[64:67], v[156:159], v[188:191], v[64:67]
	s_setprio 0
	s_barrier
	s_add_i32 s9, s9, s60
	v_lshl_add_u64 v[210:211], v[210:211], 0, s[30:31]
	s_mov_b32 m0, s9
	ds_read_b128 v[160:163], v230 offset:49152
	ds_read_b128 v[164:167], v230 offset:50176
	ds_read_b128 v[168:171], v230 offset:51200
	ds_read_b128 v[172:175], v230 offset:52224
	ds_read_b128 v[176:179], v230 offset:53248
	ds_read_b128 v[180:183], v230 offset:54272
	ds_read_b128 v[184:187], v230 offset:55296
	ds_read_b128 v[188:191], v230 offset:56320
	global_load_lds_dwordx4 v[210:211], off
	s_add_i32 m0, s9, 0x2000
	s_add_u32 s34, s56, 0x20080
	v_lshl_add_u64 v[210:211], v[212:213], 0, s[30:31]
	s_addc_u32 s35, s57, 0
	s_add_i32 s9, s33, s60
	global_load_lds_dwordx4 v[210:211], off
	v_lshl_add_u64 v[210:211], s[34:35], 0, v[196:197]
	s_mov_b32 m0, s9
	s_nop 0
	global_load_lds_dwordx4 v[210:211], off
	v_lshl_add_u64 v[210:211], s[34:35], 0, v[200:201]
	s_add_i32 m0, s9, 0x2000
	s_nop 0
	global_load_lds_dwordx4 v[210:211], off
	v_lshl_add_u64 v[210:211], v[214:215], 0, s[30:31]
	s_mov_b32 m0, s67
	s_nop 0
	global_load_lds_dwordx4 v[210:211], off
	v_lshl_add_u64 v[210:211], v[216:217], 0, s[30:31]
	s_mov_b32 m0, s68
	s_nop 0
	global_load_lds_dwordx4 v[210:211], off
	s_waitcnt vmcnt(8)
	s_waitcnt lgkmcnt(0)
	s_barrier
	s_setprio 1
	s_waitcnt lgkmcnt(0)
	v_mfma_f32_16x16x32_bf16 v[60:63], v[128:131], v[160:163], v[60:63]
	v_mfma_f32_16x16x32_bf16 v[56:59], v[136:139], v[160:163], v[56:59]
	v_mfma_f32_16x16x32_bf16 v[52:55], v[128:131], v[168:171], v[52:55]
	v_mfma_f32_16x16x32_bf16 v[48:51], v[136:139], v[168:171], v[48:51]
	v_mfma_f32_16x16x32_bf16 v[44:47], v[128:131], v[176:179], v[44:47]
	v_mfma_f32_16x16x32_bf16 v[40:43], v[136:139], v[176:179], v[40:43]
	v_mfma_f32_16x16x32_bf16 v[36:39], v[128:131], v[184:187], v[36:39]
	v_mfma_f32_16x16x32_bf16 v[32:35], v[136:139], v[184:187], v[32:35]
	v_mfma_f32_16x16x32_bf16 v[60:63], v[132:135], v[164:167], v[60:63]
	v_mfma_f32_16x16x32_bf16 v[56:59], v[140:143], v[164:167], v[56:59]
	v_mfma_f32_16x16x32_bf16 v[52:55], v[132:135], v[172:175], v[52:55]
	v_mfma_f32_16x16x32_bf16 v[48:51], v[140:143], v[172:175], v[48:51]
	v_mfma_f32_16x16x32_bf16 v[44:47], v[132:135], v[180:183], v[44:47]
	v_mfma_f32_16x16x32_bf16 v[40:43], v[140:143], v[180:183], v[40:43]
	v_mfma_f32_16x16x32_bf16 v[36:39], v[132:135], v[188:191], v[36:39]
	v_mfma_f32_16x16x32_bf16 v[32:35], v[140:143], v[188:191], v[32:35]
	v_mfma_f32_16x16x32_bf16 v[28:31], v[144:147], v[160:163], v[28:31]
	v_mfma_f32_16x16x32_bf16 v[24:27], v[152:155], v[160:163], v[24:27]
	v_mfma_f32_16x16x32_bf16 v[20:23], v[144:147], v[168:171], v[20:23]
	v_mfma_f32_16x16x32_bf16 v[16:19], v[152:155], v[168:171], v[16:19]
	v_mfma_f32_16x16x32_bf16 v[12:15], v[144:147], v[176:179], v[12:15]
	v_mfma_f32_16x16x32_bf16 v[8:11], v[152:155], v[176:179], v[8:11]
	v_mfma_f32_16x16x32_bf16 v[4:7], v[144:147], v[184:187], v[4:7]
	v_mfma_f32_16x16x32_bf16 v[0:3], v[152:155], v[184:187], v[0:3]
	v_mfma_f32_16x16x32_bf16 v[28:31], v[148:151], v[164:167], v[28:31]
	v_mfma_f32_16x16x32_bf16 v[24:27], v[156:159], v[164:167], v[24:27]
	v_mfma_f32_16x16x32_bf16 v[20:23], v[148:151], v[172:175], v[20:23]
	v_mfma_f32_16x16x32_bf16 v[16:19], v[156:159], v[172:175], v[16:19]
	v_mfma_f32_16x16x32_bf16 v[12:15], v[148:151], v[180:183], v[12:15]
	v_mfma_f32_16x16x32_bf16 v[8:11], v[156:159], v[180:183], v[8:11]
	v_mfma_f32_16x16x32_bf16 v[4:7], v[148:151], v[188:191], v[4:7]
	v_mfma_f32_16x16x32_bf16 v[0:3], v[156:159], v[188:191], v[0:3]
	s_setprio 0
	s_barrier
	s_add_i32 s7, s7, 2
	s_add_u32 s54, s54, 0x100
	s_addc_u32 s55, s55, 0
	s_add_u32 s3, s3, 0x100
	s_addc_u32 s5, s5, 0
	s_cmp_gt_u32 s7, 5
	s_cbranch_scc0 .LBB0_804
	s_and_b64 vcc, exec, s[42:43]
	s_cbranch_vccz .LBB0_807
	s_barrier

.LBB0_978:
	ds_read_b128 v[128:131], v169
	ds_read_b128 v[132:135], v169 offset:1024
	ds_read_b128 v[136:139], v169 offset:2048
	ds_read_b128 v[140:143], v169 offset:3072
	ds_read_b128 v[160:163], v170
	ds_read_b128 v[172:175], v170 offset:1024
	ds_read_b128 v[176:179], v170 offset:2048
	ds_read_b128 v[180:183], v170 offset:3072
	s_add_u32 s48, s44, 0xfffc0080
	s_addc_u32 s49, s45, -1
	s_cmp_eq_u32 s59, 12
	s_cselect_b32 s51, s31, s49
	s_cselect_b32 s50, s30, s48
	s_cselect_b32 s49, s39, s29
	s_cselect_b32 s48, s38, s27
	v_lshl_add_u64 v[164:165], s[44:45], 0, v[152:153]
	s_add_i32 m0, s7, 0xc000
	ds_read_b128 v[184:187], v171
	ds_read_b128 v[188:191], v171 offset:1024
	ds_read_b128 v[194:197], v171 offset:2048
	ds_read_b128 v[198:201], v171 offset:3072
	ds_read_b128 v[202:205], v171 offset:4096
	ds_read_b128 v[206:209], v171 offset:5120
	ds_read_b128 v[210:213], v171 offset:6144
	ds_read_b128 v[214:217], v171 offset:7168
	global_load_lds_dwordx4 v[164:165], off
	v_lshl_add_u64 v[164:165], s[44:45], 0, v[154:155]
	s_add_i32 m0, s7, 0xe000
	s_nop 0
	global_load_lds_dwordx4 v[164:165], off
	s_waitcnt vmcnt(8)
	s_waitcnt lgkmcnt(0)
	s_barrier
	s_setprio 1
	s_waitcnt lgkmcnt(0)
	v_mfma_f32_16x16x32_bf16 v[124:127], v[128:131], v[184:187], v[124:127]
	v_mfma_f32_16x16x32_bf16 v[120:123], v[136:139], v[184:187], v[120:123]
	v_mfma_f32_16x16x32_bf16 v[116:119], v[128:131], v[194:197], v[116:119]
	v_mfma_f32_16x16x32_bf16 v[112:115], v[136:139], v[194:197], v[112:115]
	v_mfma_f32_16x16x32_bf16 v[92:95], v[128:131], v[202:205], v[92:95]
	v_mfma_f32_16x16x32_bf16 v[88:91], v[136:139], v[202:205], v[88:91]
	v_mfma_f32_16x16x32_bf16 v[84:87], v[128:131], v[210:213], v[84:87]
	v_mfma_f32_16x16x32_bf16 v[76:79], v[136:139], v[210:213], v[76:79]
	v_mfma_f32_16x16x32_bf16 v[124:127], v[132:135], v[188:191], v[124:127]
	v_mfma_f32_16x16x32_bf16 v[120:123], v[140:143], v[188:191], v[120:123]
	v_mfma_f32_16x16x32_bf16 v[116:119], v[132:135], v[198:201], v[116:119]
	v_mfma_f32_16x16x32_bf16 v[112:115], v[140:143], v[198:201], v[112:115]
	v_mfma_f32_16x16x32_bf16 v[92:95], v[132:135], v[206:209], v[92:95]
	v_mfma_f32_16x16x32_bf16 v[88:91], v[140:143], v[206:209], v[88:91]
	v_mfma_f32_16x16x32_bf16 v[84:87], v[132:135], v[214:217], v[84:87]
	v_mfma_f32_16x16x32_bf16 v[76:79], v[140:143], v[214:217], v[76:79]
	v_mfma_f32_16x16x32_bf16 v[108:111], v[160:163], v[184:187], v[108:111]
	v_mfma_f32_16x16x32_bf16 v[104:107], v[176:179], v[184:187], v[104:107]
	v_mfma_f32_16x16x32_bf16 v[100:103], v[160:163], v[194:197], v[100:103]
	v_mfma_f32_16x16x32_bf16 v[96:99], v[176:179], v[194:197], v[96:99]
	v_mfma_f32_16x16x32_bf16 v[80:83], v[160:163], v[202:205], v[80:83]
	v_mfma_f32_16x16x32_bf16 v[72:75], v[176:179], v[202:205], v[72:75]
	v_mfma_f32_16x16x32_bf16 v[68:71], v[160:163], v[210:213], v[68:71]
	v_mfma_f32_16x16x32_bf16 v[64:67], v[176:179], v[210:213], v[64:67]
	v_mfma_f32_16x16x32_bf16 v[108:111], v[172:175], v[188:191], v[108:111]
	v_mfma_f32_16x16x32_bf16 v[104:107], v[180:183], v[188:191], v[104:107]
	v_mfma_f32_16x16x32_bf16 v[100:103], v[172:175], v[198:201], v[100:103]
	v_mfma_f32_16x16x32_bf16 v[96:99], v[180:183], v[198:201], v[96:99]
	v_mfma_f32_16x16x32_bf16 v[80:83], v[172:175], v[206:209], v[80:83]
	v_mfma_f32_16x16x32_bf16 v[72:75], v[180:183], v[206:209], v[72:75]
	v_mfma_f32_16x16x32_bf16 v[68:71], v[172:175], v[214:217], v[68:71]
	v_mfma_f32_16x16x32_bf16 v[64:67], v[180:183], v[214:217], v[64:67]
	s_setprio 0
	s_barrier
	s_add_i32 s60, s57, s3
	v_lshl_add_u64 v[164:165], s[48:49], 0, v[146:147]
	s_mov_b32 m0, s60
	ds_read_b128 v[184:187], v171 offset:16384
	ds_read_b128 v[188:191], v171 offset:17408
	ds_read_b128 v[194:197], v171 offset:18432
	ds_read_b128 v[198:201], v171 offset:19456
	ds_read_b128 v[202:205], v171 offset:20480
	ds_read_b128 v[206:209], v171 offset:21504
	ds_read_b128 v[210:213], v171 offset:22528
	ds_read_b128 v[214:217], v171 offset:23552
	global_load_lds_dwordx4 v[164:165], off
	s_add_i32 m0, s60, 0x2000
	s_add_u32 s60, s48, 0x40000
	v_lshl_add_u64 v[218:219], s[48:49], 0, v[150:151]
	s_addc_u32 s61, s49, 0
	s_add_i32 s62, s58, s3
	global_load_lds_dwordx4 v[218:219], off
	v_lshl_add_u64 v[220:221], s[60:61], 0, v[146:147]
	s_mov_b32 m0, s62
	v_lshl_add_u64 v[222:223], s[50:51], 0, v[148:149]
	global_load_lds_dwordx4 v[220:221], off
	v_lshl_add_u64 v[220:221], s[60:61], 0, v[150:151]
	s_add_i32 m0, s62, 0x2000
	s_nop 0
	global_load_lds_dwordx4 v[220:221], off
	v_lshl_add_u64 v[220:221], s[50:51], 0, v[144:145]
	s_mov_b32 m0, s7
	s_nop 0
	global_load_lds_dwordx4 v[220:221], off
	s_mov_b32 m0, s33
	s_nop 0
	global_load_lds_dwordx4 v[222:223], off
	s_waitcnt vmcnt(8)
	s_waitcnt lgkmcnt(0)
	s_barrier
	s_setprio 1
	s_waitcnt lgkmcnt(0)
	v_mfma_f32_16x16x32_bf16 v[60:63], v[128:131], v[184:187], v[60:63]
	v_mfma_f32_16x16x32_bf16 v[56:59], v[136:139], v[184:187], v[56:59]
	v_mfma_f32_16x16x32_bf16 v[44:47], v[128:131], v[194:197], v[44:47]
	v_mfma_f32_16x16x32_bf16 v[36:39], v[136:139], v[194:197], v[36:39]
	v_mfma_f32_16x16x32_bf16 v[20:23], v[128:131], v[202:205], v[20:23]
	v_mfma_f32_16x16x32_bf16 v[12:15], v[136:139], v[202:205], v[12:15]
	v_mfma_f32_16x16x32_bf16 v[4:7], v[128:131], v[210:213], v[4:7]
	v_mfma_f32_16x16x32_bf16 v[0:3], v[136:139], v[210:213], v[0:3]
	v_mfma_f32_16x16x32_bf16 v[60:63], v[132:135], v[188:191], v[60:63]
	v_mfma_f32_16x16x32_bf16 v[56:59], v[140:143], v[188:191], v[56:59]
	v_mfma_f32_16x16x32_bf16 v[44:47], v[132:135], v[198:201], v[44:47]
	v_mfma_f32_16x16x32_bf16 v[36:39], v[140:143], v[198:201], v[36:39]
	v_mfma_f32_16x16x32_bf16 v[20:23], v[132:135], v[206:209], v[20:23]
	v_mfma_f32_16x16x32_bf16 v[12:15], v[140:143], v[206:209], v[12:15]
	v_mfma_f32_16x16x32_bf16 v[4:7], v[132:135], v[214:217], v[4:7]
	v_mfma_f32_16x16x32_bf16 v[0:3], v[140:143], v[214:217], v[0:3]
	v_mfma_f32_16x16x32_bf16 v[40:43], v[160:163], v[184:187], v[40:43]
	v_mfma_f32_16x16x32_bf16 v[32:35], v[176:179], v[184:187], v[32:35]
	v_mfma_f32_16x16x32_bf16 v[16:19], v[160:163], v[194:197], v[16:19]
	v_mfma_f32_16x16x32_bf16 v[8:11], v[176:179], v[194:197], v[8:11]
	v_mfma_f32_16x16x32_bf16 v[52:55], v[160:163], v[202:205], v[52:55]
	v_mfma_f32_16x16x32_bf16 v[48:51], v[176:179], v[202:205], v[48:51]
	v_mfma_f32_16x16x32_bf16 v[28:31], v[160:163], v[210:213], v[28:31]
	v_mfma_f32_16x16x32_bf16 v[24:27], v[176:179], v[210:213], v[24:27]
	v_mfma_f32_16x16x32_bf16 v[40:43], v[172:175], v[188:191], v[40:43]
	v_mfma_f32_16x16x32_bf16 v[32:35], v[180:183], v[188:191], v[32:35]
	v_mfma_f32_16x16x32_bf16 v[16:19], v[172:175], v[198:201], v[16:19]
	v_mfma_f32_16x16x32_bf16 v[8:11], v[180:183], v[198:201], v[8:11]
	v_mfma_f32_16x16x32_bf16 v[52:55], v[172:175], v[206:209], v[52:55]
	v_mfma_f32_16x16x32_bf16 v[48:51], v[180:183], v[206:209], v[48:51]
	v_mfma_f32_16x16x32_bf16 v[28:31], v[172:175], v[214:217], v[28:31]
	v_mfma_f32_16x16x32_bf16 v[24:27], v[180:183], v[214:217], v[24:27]
	s_setprio 0
	s_barrier
	s_add_i32 s60, 0, 0x18000
	s_add_i32 s61, 0, 0x1c000
	v_add_u32_e32 v140, s60, v167
	v_add_u32_e32 v180, s61, v167
	ds_read_b128 v[128:131], v140
	ds_read_b128 v[132:135], v140 offset:1024
	ds_read_b128 v[136:139], v140 offset:2048
	ds_read_b128 v[140:143], v140 offset:3072
	ds_read_b128 v[160:163], v180
	ds_read_b128 v[172:175], v180 offset:1024
	ds_read_b128 v[176:179], v180 offset:2048
	ds_read_b128 v[180:183], v180 offset:3072
	s_add_u32 s50, s50, 0x40000
	s_addc_u32 s51, s51, 0
	s_mov_b32 m0, s34
	v_lshl_add_u64 v[224:225], s[50:51], 0, v[144:145]
	ds_read_b128 v[184:187], v171 offset:32768
	ds_read_b128 v[188:191], v171 offset:33792
	ds_read_b128 v[194:197], v171 offset:34816
	ds_read_b128 v[198:201], v171 offset:35840
	ds_read_b128 v[202:205], v171 offset:36864
	ds_read_b128 v[206:209], v171 offset:37888
	ds_read_b128 v[210:213], v171 offset:38912
	ds_read_b128 v[214:217], v171 offset:39936
	global_load_lds_dwordx4 v[224:225], off
	v_lshl_add_u64 v[224:225], s[50:51], 0, v[148:149]
	s_mov_b32 m0, s35
	s_nop 0
	global_load_lds_dwordx4 v[224:225], off
	s_waitcnt vmcnt(8)
	s_waitcnt lgkmcnt(0)
	s_barrier
	s_setprio 1
	s_waitcnt lgkmcnt(0)
	v_mfma_f32_16x16x32_bf16 v[124:127], v[128:131], v[184:187], v[124:127]
	v_mfma_f32_16x16x32_bf16 v[120:123], v[136:139], v[184:187], v[120:123]
	v_mfma_f32_16x16x32_bf16 v[116:119], v[128:131], v[194:197], v[116:119]
	v_mfma_f32_16x16x32_bf16 v[112:115], v[136:139], v[194:197], v[112:115]
	v_mfma_f32_16x16x32_bf16 v[92:95], v[128:131], v[202:205], v[92:95]
	v_mfma_f32_16x16x32_bf16 v[88:91], v[136:139], v[202:205], v[88:91]
	v_mfma_f32_16x16x32_bf16 v[84:87], v[128:131], v[210:213], v[84:87]
	v_mfma_f32_16x16x32_bf16 v[76:79], v[136:139], v[210:213], v[76:79]
	v_mfma_f32_16x16x32_bf16 v[124:127], v[132:135], v[188:191], v[124:127]
	v_mfma_f32_16x16x32_bf16 v[120:123], v[140:143], v[188:191], v[120:123]
	v_mfma_f32_16x16x32_bf16 v[116:119], v[132:135], v[198:201], v[116:119]
	v_mfma_f32_16x16x32_bf16 v[112:115], v[140:143], v[198:201], v[112:115]
	v_mfma_f32_16x16x32_bf16 v[92:95], v[132:135], v[206:209], v[92:95]
	v_mfma_f32_16x16x32_bf16 v[88:91], v[140:143], v[206:209], v[88:91]
	v_mfma_f32_16x16x32_bf16 v[84:87], v[132:135], v[214:217], v[84:87]
	v_mfma_f32_16x16x32_bf16 v[76:79], v[140:143], v[214:217], v[76:79]
	v_mfma_f32_16x16x32_bf16 v[108:111], v[160:163], v[184:187], v[108:111]
	v_mfma_f32_16x16x32_bf16 v[104:107], v[176:179], v[184:187], v[104:107]
	v_mfma_f32_16x16x32_bf16 v[100:103], v[160:163], v[194:197], v[100:103]
	v_mfma_f32_16x16x32_bf16 v[96:99], v[176:179], v[194:197], v[96:99]
	v_mfma_f32_16x16x32_bf16 v[80:83], v[160:163], v[202:205], v[80:83]
	v_mfma_f32_16x16x32_bf16 v[72:75], v[176:179], v[202:205], v[72:75]
	v_mfma_f32_16x16x32_bf16 v[68:71], v[160:163], v[210:213], v[68:71]
	v_mfma_f32_16x16x32_bf16 v[64:67], v[176:179], v[210:213], v[64:67]
	v_mfma_f32_16x16x32_bf16 v[108:111], v[172:175], v[188:191], v[108:111]
	v_mfma_f32_16x16x32_bf16 v[104:107], v[180:183], v[188:191], v[104:107]
	v_mfma_f32_16x16x32_bf16 v[100:103], v[172:175], v[198:201], v[100:103]
	v_mfma_f32_16x16x32_bf16 v[96:99], v[180:183], v[198:201], v[96:99]
	v_mfma_f32_16x16x32_bf16 v[80:83], v[172:175], v[206:209], v[80:83]
	v_mfma_f32_16x16x32_bf16 v[72:75], v[180:183], v[206:209], v[72:75]
	v_mfma_f32_16x16x32_bf16 v[68:71], v[172:175], v[214:217], v[68:71]
	v_mfma_f32_16x16x32_bf16 v[64:67], v[180:183], v[214:217], v[64:67]
	s_setprio 0
	s_barrier
	s_add_i32 s50, s60, s3
	v_lshl_add_u64 v[164:165], v[164:165], 0, s[8:9]
	s_mov_b32 m0, s50
	ds_read_b128 v[184:187], v171 offset:49152
	ds_read_b128 v[188:191], v171 offset:50176
	ds_read_b128 v[194:197], v171 offset:51200
	ds_read_b128 v[198:201], v171 offset:52224
	ds_read_b128 v[202:205], v171 offset:53248
	ds_read_b128 v[206:209], v171 offset:54272
	ds_read_b128 v[210:213], v171 offset:55296
	ds_read_b128 v[214:217], v171 offset:56320
	global_load_lds_dwordx4 v[164:165], off
	s_add_i32 m0, s50, 0x2000
	s_add_u32 s48, s48, 0x40080
	v_lshl_add_u64 v[164:165], v[218:219], 0, s[8:9]
	s_addc_u32 s49, s49, 0
	s_add_i32 s50, s61, s3
	global_load_lds_dwordx4 v[164:165], off
	v_lshl_add_u64 v[164:165], s[48:49], 0, v[146:147]
	s_mov_b32 m0, s50
	s_nop 0
	global_load_lds_dwordx4 v[164:165], off
	v_lshl_add_u64 v[164:165], s[48:49], 0, v[150:151]
	s_add_i32 m0, s50, 0x2000
	s_nop 0
	global_load_lds_dwordx4 v[164:165], off
	v_lshl_add_u64 v[164:165], v[220:221], 0, s[8:9]
	s_mov_b32 m0, s53
	s_nop 0
	global_load_lds_dwordx4 v[164:165], off
	v_lshl_add_u64 v[164:165], v[222:223], 0, s[8:9]
	s_mov_b32 m0, s54
	s_nop 0
	global_load_lds_dwordx4 v[164:165], off
	s_waitcnt vmcnt(8)
	s_waitcnt lgkmcnt(0)
	s_barrier
	s_setprio 1
	s_waitcnt lgkmcnt(0)
	v_mfma_f32_16x16x32_bf16 v[60:63], v[128:131], v[184:187], v[60:63]
	v_mfma_f32_16x16x32_bf16 v[56:59], v[136:139], v[184:187], v[56:59]
	v_mfma_f32_16x16x32_bf16 v[44:47], v[128:131], v[194:197], v[44:47]
	v_mfma_f32_16x16x32_bf16 v[36:39], v[136:139], v[194:197], v[36:39]
	v_mfma_f32_16x16x32_bf16 v[20:23], v[128:131], v[202:205], v[20:23]
	v_mfma_f32_16x16x32_bf16 v[12:15], v[136:139], v[202:205], v[12:15]
	v_mfma_f32_16x16x32_bf16 v[4:7], v[128:131], v[210:213], v[4:7]
	v_mfma_f32_16x16x32_bf16 v[0:3], v[136:139], v[210:213], v[0:3]
	v_mfma_f32_16x16x32_bf16 v[60:63], v[132:135], v[188:191], v[60:63]
	v_mfma_f32_16x16x32_bf16 v[56:59], v[140:143], v[188:191], v[56:59]
	v_mfma_f32_16x16x32_bf16 v[44:47], v[132:135], v[198:201], v[44:47]
	v_mfma_f32_16x16x32_bf16 v[36:39], v[140:143], v[198:201], v[36:39]
	v_mfma_f32_16x16x32_bf16 v[20:23], v[132:135], v[206:209], v[20:23]
	v_mfma_f32_16x16x32_bf16 v[12:15], v[140:143], v[206:209], v[12:15]
	v_mfma_f32_16x16x32_bf16 v[4:7], v[132:135], v[214:217], v[4:7]
	v_mfma_f32_16x16x32_bf16 v[0:3], v[140:143], v[214:217], v[0:3]
	v_mfma_f32_16x16x32_bf16 v[40:43], v[160:163], v[184:187], v[40:43]
	v_mfma_f32_16x16x32_bf16 v[32:35], v[176:179], v[184:187], v[32:35]
	v_mfma_f32_16x16x32_bf16 v[16:19], v[160:163], v[194:197], v[16:19]
	v_mfma_f32_16x16x32_bf16 v[8:11], v[176:179], v[194:197], v[8:11]
	v_mfma_f32_16x16x32_bf16 v[52:55], v[160:163], v[202:205], v[52:55]
	v_mfma_f32_16x16x32_bf16 v[48:51], v[176:179], v[202:205], v[48:51]
	v_mfma_f32_16x16x32_bf16 v[28:31], v[160:163], v[210:213], v[28:31]
	v_mfma_f32_16x16x32_bf16 v[24:27], v[176:179], v[210:213], v[24:27]
	v_mfma_f32_16x16x32_bf16 v[40:43], v[172:175], v[188:191], v[40:43]
	v_mfma_f32_16x16x32_bf16 v[32:35], v[180:183], v[188:191], v[32:35]
	v_mfma_f32_16x16x32_bf16 v[16:19], v[172:175], v[198:201], v[16:19]
	v_mfma_f32_16x16x32_bf16 v[8:11], v[180:183], v[198:201], v[8:11]
	v_mfma_f32_16x16x32_bf16 v[52:55], v[172:175], v[206:209], v[52:55]
	v_mfma_f32_16x16x32_bf16 v[48:51], v[180:183], v[206:209], v[48:51]
	v_mfma_f32_16x16x32_bf16 v[28:31], v[172:175], v[214:217], v[28:31]
	v_mfma_f32_16x16x32_bf16 v[24:27], v[180:183], v[214:217], v[24:27]
	s_setprio 0
	s_barrier
	s_add_i32 s59, s59, 2
	s_add_u32 s44, s44, 0x100
	s_addc_u32 s45, s45, 0
	s_add_u32 s27, s27, 0x100
	s_addc_u32 s29, s29, 0
	s_cmp_gt_u32 s59, 13
	s_cbranch_scc0 .LBB0_978
	s_and_b64 vcc, exec, s[24:25]
	s_cbranch_vccz .LBB0_981
	s_barrier

.LBB0_1101:
	ds_read_b128 v[156:159], v153
	ds_read_b128 v[160:163], v153 offset:1024
	ds_read_b128 v[164:167], v153 offset:2048
	ds_read_b128 v[168:171], v153 offset:3072
	ds_read_b128 v[172:175], v154
	ds_read_b128 v[176:179], v154 offset:1024
	ds_read_b128 v[180:183], v154 offset:2048
	ds_read_b128 v[184:187], v154 offset:3072
	s_add_u32 s44, s42, 0xfffc0080
	s_addc_u32 s45, s43, -1
	s_cmp_eq_u32 s55, 12
	s_cselect_b32 s47, s31, s45
	s_cselect_b32 s46, s30, s44
	s_cselect_b32 s45, s37, s29
	s_cselect_b32 s44, s36, s27
	v_lshl_add_u64 v[148:149], s[42:43], 0, v[138:139]
	s_add_i32 m0, s33, 0xc000
	ds_read_b128 v[188:191], v155
	ds_read_b128 v[194:197], v155 offset:1024
	ds_read_b128 v[198:201], v155 offset:2048
	ds_read_b128 v[202:205], v155 offset:3072
	ds_read_b128 v[206:209], v155 offset:4096
	ds_read_b128 v[210:213], v155 offset:5120
	ds_read_b128 v[214:217], v155 offset:6144
	ds_read_b128 v[218:221], v155 offset:7168
	global_load_lds_dwordx4 v[148:149], off
	v_lshl_add_u64 v[148:149], s[42:43], 0, v[140:141]
	s_add_i32 m0, s33, 0xe000
	s_nop 0
	global_load_lds_dwordx4 v[148:149], off
	s_waitcnt vmcnt(8)
	s_waitcnt lgkmcnt(0)
	s_barrier
	s_setprio 1
	s_waitcnt lgkmcnt(0)
	v_mfma_f32_16x16x32_bf16 v[124:127], v[156:159], v[188:191], v[124:127]
	v_mfma_f32_16x16x32_bf16 v[120:123], v[164:167], v[188:191], v[120:123]
	v_mfma_f32_16x16x32_bf16 v[108:111], v[156:159], v[198:201], v[108:111]
	v_mfma_f32_16x16x32_bf16 v[104:107], v[164:167], v[198:201], v[104:107]
	v_mfma_f32_16x16x32_bf16 v[92:95], v[156:159], v[206:209], v[92:95]
	v_mfma_f32_16x16x32_bf16 v[88:91], v[164:167], v[206:209], v[88:91]
	v_mfma_f32_16x16x32_bf16 v[76:79], v[156:159], v[214:217], v[76:79]
	v_mfma_f32_16x16x32_bf16 v[72:75], v[164:167], v[214:217], v[72:75]
	v_mfma_f32_16x16x32_bf16 v[124:127], v[160:163], v[194:197], v[124:127]
	v_mfma_f32_16x16x32_bf16 v[120:123], v[168:171], v[194:197], v[120:123]
	v_mfma_f32_16x16x32_bf16 v[108:111], v[160:163], v[202:205], v[108:111]
	v_mfma_f32_16x16x32_bf16 v[104:107], v[168:171], v[202:205], v[104:107]
	v_mfma_f32_16x16x32_bf16 v[92:95], v[160:163], v[210:213], v[92:95]
	v_mfma_f32_16x16x32_bf16 v[88:91], v[168:171], v[210:213], v[88:91]
	v_mfma_f32_16x16x32_bf16 v[76:79], v[160:163], v[218:221], v[76:79]
	v_mfma_f32_16x16x32_bf16 v[72:75], v[168:171], v[218:221], v[72:75]
	v_mfma_f32_16x16x32_bf16 v[116:119], v[172:175], v[188:191], v[116:119]
	v_mfma_f32_16x16x32_bf16 v[112:115], v[180:183], v[188:191], v[112:115]
	v_mfma_f32_16x16x32_bf16 v[100:103], v[172:175], v[198:201], v[100:103]
	v_mfma_f32_16x16x32_bf16 v[96:99], v[180:183], v[198:201], v[96:99]
	v_mfma_f32_16x16x32_bf16 v[84:87], v[172:175], v[206:209], v[84:87]
	v_mfma_f32_16x16x32_bf16 v[80:83], v[180:183], v[206:209], v[80:83]
	v_mfma_f32_16x16x32_bf16 v[68:71], v[172:175], v[214:217], v[68:71]
	v_mfma_f32_16x16x32_bf16 v[64:67], v[180:183], v[214:217], v[64:67]
	v_mfma_f32_16x16x32_bf16 v[116:119], v[176:179], v[194:197], v[116:119]
	v_mfma_f32_16x16x32_bf16 v[112:115], v[184:187], v[194:197], v[112:115]
	v_mfma_f32_16x16x32_bf16 v[100:103], v[176:179], v[202:205], v[100:103]
	v_mfma_f32_16x16x32_bf16 v[96:99], v[184:187], v[202:205], v[96:99]
	v_mfma_f32_16x16x32_bf16 v[84:87], v[176:179], v[210:213], v[84:87]
	v_mfma_f32_16x16x32_bf16 v[80:83], v[184:187], v[210:213], v[80:83]
	v_mfma_f32_16x16x32_bf16 v[68:71], v[176:179], v[218:221], v[68:71]
	v_mfma_f32_16x16x32_bf16 v[64:67], v[184:187], v[218:221], v[64:67]
	s_setprio 0
	s_barrier
	s_add_i32 s56, s52, s2
	v_lshl_add_u64 v[148:149], s[44:45], 0, v[132:133]
	s_mov_b32 m0, s56
	ds_read_b128 v[188:191], v155 offset:16384
	ds_read_b128 v[194:197], v155 offset:17408
	ds_read_b128 v[198:201], v155 offset:18432
	ds_read_b128 v[202:205], v155 offset:19456
	ds_read_b128 v[206:209], v155 offset:20480
	ds_read_b128 v[210:213], v155 offset:21504
	ds_read_b128 v[214:217], v155 offset:22528
	ds_read_b128 v[218:221], v155 offset:23552
	global_load_lds_dwordx4 v[148:149], off
	s_add_i32 m0, s56, 0x2000
	s_add_u32 s56, s44, 0x40000
	v_lshl_add_u64 v[222:223], s[44:45], 0, v[128:129]
	s_addc_u32 s57, s45, 0
	s_add_i32 s58, s53, s2
	global_load_lds_dwordx4 v[222:223], off
	v_lshl_add_u64 v[224:225], s[56:57], 0, v[132:133]
	s_mov_b32 m0, s58
	v_lshl_add_u64 v[228:229], s[46:47], 0, v[130:131]
	global_load_lds_dwordx4 v[224:225], off
	v_lshl_add_u64 v[224:225], s[56:57], 0, v[128:129]
	s_add_i32 m0, s58, 0x2000
	s_nop 0
	global_load_lds_dwordx4 v[224:225], off
	v_lshl_add_u64 v[224:225], s[46:47], 0, v[134:135]
	s_mov_b32 m0, s33
	s_nop 0
	global_load_lds_dwordx4 v[224:225], off
	s_mov_b32 m0, s34
	s_nop 0
	global_load_lds_dwordx4 v[228:229], off
	s_waitcnt vmcnt(8)
	s_waitcnt lgkmcnt(0)
	s_barrier
	s_setprio 1
	s_waitcnt lgkmcnt(0)
	v_mfma_f32_16x16x32_bf16 v[60:63], v[156:159], v[188:191], v[60:63]
	v_mfma_f32_16x16x32_bf16 v[56:59], v[164:167], v[188:191], v[56:59]
	v_mfma_f32_16x16x32_bf16 v[44:47], v[156:159], v[198:201], v[44:47]
	v_mfma_f32_16x16x32_bf16 v[40:43], v[164:167], v[198:201], v[40:43]
	v_mfma_f32_16x16x32_bf16 v[28:31], v[156:159], v[206:209], v[28:31]
	v_mfma_f32_16x16x32_bf16 v[24:27], v[164:167], v[206:209], v[24:27]
	v_mfma_f32_16x16x32_bf16 v[12:15], v[156:159], v[214:217], v[12:15]
	v_mfma_f32_16x16x32_bf16 v[8:11], v[164:167], v[214:217], v[8:11]
	v_mfma_f32_16x16x32_bf16 v[60:63], v[160:163], v[194:197], v[60:63]
	v_mfma_f32_16x16x32_bf16 v[56:59], v[168:171], v[194:197], v[56:59]
	v_mfma_f32_16x16x32_bf16 v[44:47], v[160:163], v[202:205], v[44:47]
	v_mfma_f32_16x16x32_bf16 v[40:43], v[168:171], v[202:205], v[40:43]
	v_mfma_f32_16x16x32_bf16 v[28:31], v[160:163], v[210:213], v[28:31]
	v_mfma_f32_16x16x32_bf16 v[24:27], v[168:171], v[210:213], v[24:27]
	v_mfma_f32_16x16x32_bf16 v[12:15], v[160:163], v[218:221], v[12:15]
	v_mfma_f32_16x16x32_bf16 v[8:11], v[168:171], v[218:221], v[8:11]
	v_mfma_f32_16x16x32_bf16 v[52:55], v[172:175], v[188:191], v[52:55]
	v_mfma_f32_16x16x32_bf16 v[48:51], v[180:183], v[188:191], v[48:51]
	v_mfma_f32_16x16x32_bf16 v[36:39], v[172:175], v[198:201], v[36:39]
	v_mfma_f32_16x16x32_bf16 v[32:35], v[180:183], v[198:201], v[32:35]
	v_mfma_f32_16x16x32_bf16 v[20:23], v[172:175], v[206:209], v[20:23]
	v_mfma_f32_16x16x32_bf16 v[16:19], v[180:183], v[206:209], v[16:19]
	v_mfma_f32_16x16x32_bf16 v[4:7], v[172:175], v[214:217], v[4:7]
	v_mfma_f32_16x16x32_bf16 v[0:3], v[180:183], v[214:217], v[0:3]
	v_mfma_f32_16x16x32_bf16 v[52:55], v[176:179], v[194:197], v[52:55]
	v_mfma_f32_16x16x32_bf16 v[48:51], v[184:187], v[194:197], v[48:51]
	v_mfma_f32_16x16x32_bf16 v[36:39], v[176:179], v[202:205], v[36:39]
	v_mfma_f32_16x16x32_bf16 v[32:35], v[184:187], v[202:205], v[32:35]
	v_mfma_f32_16x16x32_bf16 v[20:23], v[176:179], v[210:213], v[20:23]
	v_mfma_f32_16x16x32_bf16 v[16:19], v[184:187], v[210:213], v[16:19]
	v_mfma_f32_16x16x32_bf16 v[4:7], v[176:179], v[218:221], v[4:7]
	v_mfma_f32_16x16x32_bf16 v[0:3], v[184:187], v[218:221], v[0:3]
	s_setprio 0
	s_barrier
	s_add_i32 s56, 0, 0x18000
	v_add_u32_e32 v136, s56, v151
	s_add_i32 s57, 0, 0x1c000
	ds_read_b128 v[156:159], v136
	ds_read_b128 v[160:163], v136 offset:1024
	ds_read_b128 v[164:167], v136 offset:2048
	ds_read_b128 v[168:171], v136 offset:3072
	v_add_u32_e32 v136, s57, v151
	ds_read_b128 v[172:175], v136
	ds_read_b128 v[176:179], v136 offset:1024
	ds_read_b128 v[180:183], v136 offset:2048
	ds_read_b128 v[184:187], v136 offset:3072
	s_add_u32 s46, s46, 0x40000
	s_addc_u32 s47, s47, 0
	s_mov_b32 m0, s35
	v_lshl_add_u64 v[230:231], s[46:47], 0, v[134:135]
	ds_read_b128 v[188:191], v155 offset:32768
	ds_read_b128 v[194:197], v155 offset:33792
	ds_read_b128 v[198:201], v155 offset:34816
	ds_read_b128 v[202:205], v155 offset:35840
	ds_read_b128 v[206:209], v155 offset:36864
	ds_read_b128 v[210:213], v155 offset:37888
	ds_read_b128 v[214:217], v155 offset:38912
	ds_read_b128 v[218:221], v155 offset:39936
	global_load_lds_dwordx4 v[230:231], off
	v_lshl_add_u64 v[230:231], s[46:47], 0, v[130:131]
	s_mov_b32 m0, s39
	s_nop 0
	global_load_lds_dwordx4 v[230:231], off
	s_waitcnt vmcnt(8)
	s_waitcnt lgkmcnt(0)
	s_barrier
	s_setprio 1
	s_waitcnt lgkmcnt(0)
	v_mfma_f32_16x16x32_bf16 v[124:127], v[156:159], v[188:191], v[124:127]
	v_mfma_f32_16x16x32_bf16 v[120:123], v[164:167], v[188:191], v[120:123]
	v_mfma_f32_16x16x32_bf16 v[108:111], v[156:159], v[198:201], v[108:111]
	v_mfma_f32_16x16x32_bf16 v[104:107], v[164:167], v[198:201], v[104:107]
	v_mfma_f32_16x16x32_bf16 v[92:95], v[156:159], v[206:209], v[92:95]
	v_mfma_f32_16x16x32_bf16 v[88:91], v[164:167], v[206:209], v[88:91]
	v_mfma_f32_16x16x32_bf16 v[76:79], v[156:159], v[214:217], v[76:79]
	v_mfma_f32_16x16x32_bf16 v[72:75], v[164:167], v[214:217], v[72:75]
	v_mfma_f32_16x16x32_bf16 v[124:127], v[160:163], v[194:197], v[124:127]
	v_mfma_f32_16x16x32_bf16 v[120:123], v[168:171], v[194:197], v[120:123]
	v_mfma_f32_16x16x32_bf16 v[108:111], v[160:163], v[202:205], v[108:111]
	v_mfma_f32_16x16x32_bf16 v[104:107], v[168:171], v[202:205], v[104:107]
	v_mfma_f32_16x16x32_bf16 v[92:95], v[160:163], v[210:213], v[92:95]
	v_mfma_f32_16x16x32_bf16 v[88:91], v[168:171], v[210:213], v[88:91]
	v_mfma_f32_16x16x32_bf16 v[76:79], v[160:163], v[218:221], v[76:79]
	v_mfma_f32_16x16x32_bf16 v[72:75], v[168:171], v[218:221], v[72:75]
	v_mfma_f32_16x16x32_bf16 v[116:119], v[172:175], v[188:191], v[116:119]
	v_mfma_f32_16x16x32_bf16 v[112:115], v[180:183], v[188:191], v[112:115]
	v_mfma_f32_16x16x32_bf16 v[100:103], v[172:175], v[198:201], v[100:103]
	v_mfma_f32_16x16x32_bf16 v[96:99], v[180:183], v[198:201], v[96:99]
	v_mfma_f32_16x16x32_bf16 v[84:87], v[172:175], v[206:209], v[84:87]
	v_mfma_f32_16x16x32_bf16 v[80:83], v[180:183], v[206:209], v[80:83]
	v_mfma_f32_16x16x32_bf16 v[68:71], v[172:175], v[214:217], v[68:71]
	v_mfma_f32_16x16x32_bf16 v[64:67], v[180:183], v[214:217], v[64:67]
	v_mfma_f32_16x16x32_bf16 v[116:119], v[176:179], v[194:197], v[116:119]
	v_mfma_f32_16x16x32_bf16 v[112:115], v[184:187], v[194:197], v[112:115]
	v_mfma_f32_16x16x32_bf16 v[100:103], v[176:179], v[202:205], v[100:103]
	v_mfma_f32_16x16x32_bf16 v[96:99], v[184:187], v[202:205], v[96:99]
	v_mfma_f32_16x16x32_bf16 v[84:87], v[176:179], v[210:213], v[84:87]
	v_mfma_f32_16x16x32_bf16 v[80:83], v[184:187], v[210:213], v[80:83]
	v_mfma_f32_16x16x32_bf16 v[68:71], v[176:179], v[218:221], v[68:71]
	v_mfma_f32_16x16x32_bf16 v[64:67], v[184:187], v[218:221], v[64:67]
	s_setprio 0
	s_barrier
	s_add_i32 s46, s56, s2
	v_lshl_add_u64 v[148:149], v[148:149], 0, s[12:13]
	s_mov_b32 m0, s46
	ds_read_b128 v[188:191], v155 offset:49152
	ds_read_b128 v[194:197], v155 offset:50176
	ds_read_b128 v[198:201], v155 offset:51200
	ds_read_b128 v[202:205], v155 offset:52224
	ds_read_b128 v[206:209], v155 offset:53248
	ds_read_b128 v[210:213], v155 offset:54272
	ds_read_b128 v[214:217], v155 offset:55296
	ds_read_b128 v[218:221], v155 offset:56320
	global_load_lds_dwordx4 v[148:149], off
	s_add_i32 m0, s46, 0x2000
	s_add_u32 s44, s44, 0x40080
	v_lshl_add_u64 v[148:149], v[222:223], 0, s[12:13]
	s_addc_u32 s45, s45, 0
	s_add_i32 s46, s57, s2
	global_load_lds_dwordx4 v[148:149], off
	v_lshl_add_u64 v[148:149], s[44:45], 0, v[132:133]
	s_mov_b32 m0, s46
	s_nop 0
	global_load_lds_dwordx4 v[148:149], off
	v_lshl_add_u64 v[148:149], s[44:45], 0, v[128:129]
	s_add_i32 m0, s46, 0x2000
	s_nop 0
	global_load_lds_dwordx4 v[148:149], off
	v_lshl_add_u64 v[148:149], v[224:225], 0, s[12:13]
	s_mov_b32 m0, s48
	s_nop 0
	global_load_lds_dwordx4 v[148:149], off
	v_lshl_add_u64 v[148:149], v[228:229], 0, s[12:13]
	s_mov_b32 m0, s49
	s_nop 0
	global_load_lds_dwordx4 v[148:149], off
	s_waitcnt vmcnt(8)
	s_waitcnt lgkmcnt(0)
	s_barrier
	s_setprio 1
	s_waitcnt lgkmcnt(0)
	v_mfma_f32_16x16x32_bf16 v[60:63], v[156:159], v[188:191], v[60:63]
	v_mfma_f32_16x16x32_bf16 v[56:59], v[164:167], v[188:191], v[56:59]
	v_mfma_f32_16x16x32_bf16 v[44:47], v[156:159], v[198:201], v[44:47]
	v_mfma_f32_16x16x32_bf16 v[40:43], v[164:167], v[198:201], v[40:43]
	v_mfma_f32_16x16x32_bf16 v[28:31], v[156:159], v[206:209], v[28:31]
	v_mfma_f32_16x16x32_bf16 v[24:27], v[164:167], v[206:209], v[24:27]
	v_mfma_f32_16x16x32_bf16 v[12:15], v[156:159], v[214:217], v[12:15]
	v_mfma_f32_16x16x32_bf16 v[8:11], v[164:167], v[214:217], v[8:11]
	v_mfma_f32_16x16x32_bf16 v[60:63], v[160:163], v[194:197], v[60:63]
	v_mfma_f32_16x16x32_bf16 v[56:59], v[168:171], v[194:197], v[56:59]
	v_mfma_f32_16x16x32_bf16 v[44:47], v[160:163], v[202:205], v[44:47]
	v_mfma_f32_16x16x32_bf16 v[40:43], v[168:171], v[202:205], v[40:43]
	v_mfma_f32_16x16x32_bf16 v[28:31], v[160:163], v[210:213], v[28:31]
	v_mfma_f32_16x16x32_bf16 v[24:27], v[168:171], v[210:213], v[24:27]
	v_mfma_f32_16x16x32_bf16 v[12:15], v[160:163], v[218:221], v[12:15]
	v_mfma_f32_16x16x32_bf16 v[8:11], v[168:171], v[218:221], v[8:11]
	v_mfma_f32_16x16x32_bf16 v[52:55], v[172:175], v[188:191], v[52:55]
	v_mfma_f32_16x16x32_bf16 v[48:51], v[180:183], v[188:191], v[48:51]
	v_mfma_f32_16x16x32_bf16 v[36:39], v[172:175], v[198:201], v[36:39]
	v_mfma_f32_16x16x32_bf16 v[32:35], v[180:183], v[198:201], v[32:35]
	v_mfma_f32_16x16x32_bf16 v[20:23], v[172:175], v[206:209], v[20:23]
	v_mfma_f32_16x16x32_bf16 v[16:19], v[180:183], v[206:209], v[16:19]
	v_mfma_f32_16x16x32_bf16 v[4:7], v[172:175], v[214:217], v[4:7]
	v_mfma_f32_16x16x32_bf16 v[0:3], v[180:183], v[214:217], v[0:3]
	v_mfma_f32_16x16x32_bf16 v[52:55], v[176:179], v[194:197], v[52:55]
	v_mfma_f32_16x16x32_bf16 v[48:51], v[184:187], v[194:197], v[48:51]
	v_mfma_f32_16x16x32_bf16 v[36:39], v[176:179], v[202:205], v[36:39]
	v_mfma_f32_16x16x32_bf16 v[32:35], v[184:187], v[202:205], v[32:35]
	v_mfma_f32_16x16x32_bf16 v[20:23], v[176:179], v[210:213], v[20:23]
	v_mfma_f32_16x16x32_bf16 v[16:19], v[184:187], v[210:213], v[16:19]
	v_mfma_f32_16x16x32_bf16 v[4:7], v[176:179], v[218:221], v[4:7]
	v_mfma_f32_16x16x32_bf16 v[0:3], v[184:187], v[218:221], v[0:3]
	s_setprio 0
	s_barrier
	s_add_i32 s55, s55, 2
	s_add_u32 s42, s42, 0x100
	s_addc_u32 s43, s43, 0
	s_add_u32 s27, s27, 0x100
	s_addc_u32 s29, s29, 0
	s_cmp_gt_u32 s55, 13
	s_cbranch_scc0 .LBB0_1101
	s_and_b64 vcc, exec, s[24:25]
	s_cbranch_vccz .LBB0_1104
	s_barrier

.LBB0_1177:
	ds_read_b128 v[128:131], v171
	ds_read_b128 v[132:135], v171 offset:1024
	ds_read_b128 v[136:139], v171 offset:2048
	ds_read_b128 v[140:143], v171 offset:3072
	ds_read_b128 v[162:165], v172
	ds_read_b128 v[174:177], v172 offset:1024
	ds_read_b128 v[178:181], v172 offset:2048
	ds_read_b128 v[182:185], v172 offset:3072
	s_add_u32 s28, s26, 0x100
	s_addc_u32 s29, s27, 0
	s_cmp_eq_u32 s53, 40
	s_cselect_b32 s37, s17, s29
	s_cselect_b32 s36, s16, s28
	s_cselect_b32 s31, s25, s52
	s_cselect_b32 s30, s24, s51
	v_lshl_add_u64 v[166:167], s[26:27], 0, v[154:155]
	s_add_i32 m0, s7, 0xc000
	ds_read_b128 v[186:189], v173
	ds_read_b128 v[194:197], v173 offset:1024
	ds_read_b128 v[198:201], v173 offset:2048
	ds_read_b128 v[202:205], v173 offset:3072
	ds_read_b128 v[206:209], v173 offset:4096
	ds_read_b128 v[210:213], v173 offset:5120
	ds_read_b128 v[214:217], v173 offset:6144
	ds_read_b128 v[218:221], v173 offset:7168
	global_load_lds_dwordx4 v[166:167], off
	v_lshl_add_u64 v[166:167], s[26:27], 0, v[156:157]
	s_add_i32 m0, s7, 0xe000
	s_nop 0
	global_load_lds_dwordx4 v[166:167], off
	s_waitcnt vmcnt(8)
	s_waitcnt lgkmcnt(0)
	s_barrier
	s_setprio 1
	s_waitcnt lgkmcnt(0)
	v_mfma_f32_16x16x32_bf16 v[124:127], v[128:131], v[186:189], v[124:127]
	v_mfma_f32_16x16x32_bf16 v[120:123], v[136:139], v[186:189], v[120:123]
	v_mfma_f32_16x16x32_bf16 v[112:115], v[128:131], v[198:201], v[112:115]
	v_mfma_f32_16x16x32_bf16 v[104:107], v[136:139], v[198:201], v[104:107]
	v_mfma_f32_16x16x32_bf16 v[96:99], v[128:131], v[206:209], v[96:99]
	v_mfma_f32_16x16x32_bf16 v[88:91], v[136:139], v[206:209], v[88:91]
	v_mfma_f32_16x16x32_bf16 v[80:83], v[128:131], v[214:217], v[80:83]
	v_mfma_f32_16x16x32_bf16 v[72:75], v[136:139], v[214:217], v[72:75]
	v_mfma_f32_16x16x32_bf16 v[124:127], v[132:135], v[194:197], v[124:127]
	v_mfma_f32_16x16x32_bf16 v[120:123], v[140:143], v[194:197], v[120:123]
	v_mfma_f32_16x16x32_bf16 v[112:115], v[132:135], v[202:205], v[112:115]
	v_mfma_f32_16x16x32_bf16 v[104:107], v[140:143], v[202:205], v[104:107]
	v_mfma_f32_16x16x32_bf16 v[96:99], v[132:135], v[210:213], v[96:99]
	v_mfma_f32_16x16x32_bf16 v[88:91], v[140:143], v[210:213], v[88:91]
	v_mfma_f32_16x16x32_bf16 v[80:83], v[132:135], v[218:221], v[80:83]
	v_mfma_f32_16x16x32_bf16 v[72:75], v[140:143], v[218:221], v[72:75]
	v_mfma_f32_16x16x32_bf16 v[116:119], v[162:165], v[186:189], v[116:119]
	v_mfma_f32_16x16x32_bf16 v[108:111], v[178:181], v[186:189], v[108:111]
	v_mfma_f32_16x16x32_bf16 v[100:103], v[162:165], v[198:201], v[100:103]
	v_mfma_f32_16x16x32_bf16 v[92:95], v[178:181], v[198:201], v[92:95]
	v_mfma_f32_16x16x32_bf16 v[84:87], v[162:165], v[206:209], v[84:87]
	v_mfma_f32_16x16x32_bf16 v[76:79], v[178:181], v[206:209], v[76:79]
	v_mfma_f32_16x16x32_bf16 v[68:71], v[162:165], v[214:217], v[68:71]
	v_mfma_f32_16x16x32_bf16 v[64:67], v[178:181], v[214:217], v[64:67]
	v_mfma_f32_16x16x32_bf16 v[116:119], v[174:177], v[194:197], v[116:119]
	v_mfma_f32_16x16x32_bf16 v[108:111], v[182:185], v[194:197], v[108:111]
	v_mfma_f32_16x16x32_bf16 v[100:103], v[174:177], v[202:205], v[100:103]
	v_mfma_f32_16x16x32_bf16 v[92:95], v[182:185], v[202:205], v[92:95]
	v_mfma_f32_16x16x32_bf16 v[84:87], v[174:177], v[210:213], v[84:87]
	v_mfma_f32_16x16x32_bf16 v[76:79], v[182:185], v[210:213], v[76:79]
	v_mfma_f32_16x16x32_bf16 v[68:71], v[174:177], v[218:221], v[68:71]
	v_mfma_f32_16x16x32_bf16 v[64:67], v[182:185], v[218:221], v[64:67]
	s_setprio 0
	s_barrier
	s_add_i32 s26, s45, s3
	v_lshl_add_u64 v[166:167], s[30:31], 0, v[148:149]
	s_mov_b32 m0, s26
	ds_read_b128 v[186:189], v173 offset:16384
	ds_read_b128 v[194:197], v173 offset:17408
	ds_read_b128 v[198:201], v173 offset:18432
	ds_read_b128 v[202:205], v173 offset:19456
	ds_read_b128 v[206:209], v173 offset:20480
	ds_read_b128 v[210:213], v173 offset:21504
	ds_read_b128 v[214:217], v173 offset:22528
	ds_read_b128 v[218:221], v173 offset:23552
	global_load_lds_dwordx4 v[166:167], off
	s_add_i32 m0, s26, 0x2000
	s_add_u32 s26, s30, 0xb0000
	v_lshl_add_u64 v[190:191], s[30:31], 0, v[152:153]
	s_addc_u32 s27, s31, 0
	s_add_i32 s54, s46, s3
	global_load_lds_dwordx4 v[190:191], off
	v_lshl_add_u64 v[222:223], s[26:27], 0, v[148:149]
	s_mov_b32 m0, s54
	v_lshl_add_u64 v[224:225], s[36:37], 0, v[150:151]
	global_load_lds_dwordx4 v[222:223], off
	v_lshl_add_u64 v[222:223], s[26:27], 0, v[152:153]
	s_add_i32 m0, s54, 0x2000
	s_nop 0
	global_load_lds_dwordx4 v[222:223], off
	v_lshl_add_u64 v[222:223], s[36:37], 0, v[146:147]
	s_mov_b32 m0, s7
	s_nop 0
	global_load_lds_dwordx4 v[222:223], off
	s_mov_b32 m0, s33
	s_nop 0
	global_load_lds_dwordx4 v[224:225], off
	s_waitcnt vmcnt(8)
	s_waitcnt lgkmcnt(0)
	s_barrier
	s_setprio 1
	s_waitcnt lgkmcnt(0)
	v_mfma_f32_16x16x32_bf16 v[60:63], v[128:131], v[186:189], v[60:63]
	v_mfma_f32_16x16x32_bf16 v[56:59], v[136:139], v[186:189], v[56:59]
	v_mfma_f32_16x16x32_bf16 v[48:51], v[128:131], v[198:201], v[48:51]
	v_mfma_f32_16x16x32_bf16 v[32:35], v[136:139], v[198:201], v[32:35]
	v_mfma_f32_16x16x32_bf16 v[16:19], v[128:131], v[206:209], v[16:19]
	v_mfma_f32_16x16x32_bf16 v[12:15], v[136:139], v[206:209], v[12:15]
	v_mfma_f32_16x16x32_bf16 v[4:7], v[128:131], v[214:217], v[4:7]
	v_mfma_f32_16x16x32_bf16 v[0:3], v[136:139], v[214:217], v[0:3]
	v_mfma_f32_16x16x32_bf16 v[60:63], v[132:135], v[194:197], v[60:63]
	v_mfma_f32_16x16x32_bf16 v[56:59], v[140:143], v[194:197], v[56:59]
	v_mfma_f32_16x16x32_bf16 v[48:51], v[132:135], v[202:205], v[48:51]
	v_mfma_f32_16x16x32_bf16 v[32:35], v[140:143], v[202:205], v[32:35]
	v_mfma_f32_16x16x32_bf16 v[16:19], v[132:135], v[210:213], v[16:19]
	v_mfma_f32_16x16x32_bf16 v[12:15], v[140:143], v[210:213], v[12:15]
	v_mfma_f32_16x16x32_bf16 v[4:7], v[132:135], v[218:221], v[4:7]
	v_mfma_f32_16x16x32_bf16 v[0:3], v[140:143], v[218:221], v[0:3]
	v_mfma_f32_16x16x32_bf16 v[52:55], v[162:165], v[186:189], v[52:55]
	v_mfma_f32_16x16x32_bf16 v[36:39], v[178:181], v[186:189], v[36:39]
	v_mfma_f32_16x16x32_bf16 v[20:23], v[162:165], v[198:201], v[20:23]
	v_mfma_f32_16x16x32_bf16 v[8:11], v[178:181], v[198:201], v[8:11]
	v_mfma_f32_16x16x32_bf16 v[44:47], v[162:165], v[206:209], v[44:47]
	v_mfma_f32_16x16x32_bf16 v[40:43], v[178:181], v[206:209], v[40:43]
	v_mfma_f32_16x16x32_bf16 v[28:31], v[162:165], v[214:217], v[28:31]
	v_mfma_f32_16x16x32_bf16 v[24:27], v[178:181], v[214:217], v[24:27]
	v_mfma_f32_16x16x32_bf16 v[52:55], v[174:177], v[194:197], v[52:55]
	v_mfma_f32_16x16x32_bf16 v[36:39], v[182:185], v[194:197], v[36:39]
	v_mfma_f32_16x16x32_bf16 v[20:23], v[174:177], v[202:205], v[20:23]
	v_mfma_f32_16x16x32_bf16 v[8:11], v[182:185], v[202:205], v[8:11]
	v_mfma_f32_16x16x32_bf16 v[44:47], v[174:177], v[210:213], v[44:47]
	v_mfma_f32_16x16x32_bf16 v[40:43], v[182:185], v[210:213], v[40:43]
	v_mfma_f32_16x16x32_bf16 v[28:31], v[174:177], v[218:221], v[28:31]
	v_mfma_f32_16x16x32_bf16 v[24:27], v[182:185], v[218:221], v[24:27]
	s_setprio 0
	s_barrier
	s_add_i32 s54, 0, 0x18000
	s_add_i32 s55, 0, 0x1c000
	v_add_u32_e32 v140, s54, v169
	v_add_u32_e32 v182, s55, v169
	ds_read_b128 v[128:131], v140
	ds_read_b128 v[132:135], v140 offset:1024
	ds_read_b128 v[136:139], v140 offset:2048
	ds_read_b128 v[140:143], v140 offset:3072
	ds_read_b128 v[162:165], v182
	ds_read_b128 v[174:177], v182 offset:1024
	ds_read_b128 v[178:181], v182 offset:2048
	ds_read_b128 v[182:185], v182 offset:3072
	s_add_u32 s26, s36, 0xb0000
	s_addc_u32 s27, s37, 0
	s_mov_b32 m0, s34
	v_lshl_add_u64 v[228:229], s[26:27], 0, v[146:147]
	ds_read_b128 v[186:189], v173 offset:32768
	ds_read_b128 v[194:197], v173 offset:33792
	ds_read_b128 v[198:201], v173 offset:34816
	ds_read_b128 v[202:205], v173 offset:35840
	ds_read_b128 v[206:209], v173 offset:36864
	ds_read_b128 v[210:213], v173 offset:37888
	ds_read_b128 v[214:217], v173 offset:38912
	ds_read_b128 v[218:221], v173 offset:39936
	global_load_lds_dwordx4 v[228:229], off
	v_lshl_add_u64 v[228:229], s[26:27], 0, v[150:151]
	s_mov_b32 m0, s35
	s_nop 0
	global_load_lds_dwordx4 v[228:229], off
	s_waitcnt vmcnt(8)
	s_waitcnt lgkmcnt(0)
	s_barrier
	s_setprio 1
	s_waitcnt lgkmcnt(0)
	v_mfma_f32_16x16x32_bf16 v[124:127], v[128:131], v[186:189], v[124:127]
	v_mfma_f32_16x16x32_bf16 v[120:123], v[136:139], v[186:189], v[120:123]
	v_mfma_f32_16x16x32_bf16 v[112:115], v[128:131], v[198:201], v[112:115]
	v_mfma_f32_16x16x32_bf16 v[104:107], v[136:139], v[198:201], v[104:107]
	v_mfma_f32_16x16x32_bf16 v[96:99], v[128:131], v[206:209], v[96:99]
	v_mfma_f32_16x16x32_bf16 v[88:91], v[136:139], v[206:209], v[88:91]
	v_mfma_f32_16x16x32_bf16 v[80:83], v[128:131], v[214:217], v[80:83]
	v_mfma_f32_16x16x32_bf16 v[72:75], v[136:139], v[214:217], v[72:75]
	v_mfma_f32_16x16x32_bf16 v[124:127], v[132:135], v[194:197], v[124:127]
	v_mfma_f32_16x16x32_bf16 v[120:123], v[140:143], v[194:197], v[120:123]
	v_mfma_f32_16x16x32_bf16 v[112:115], v[132:135], v[202:205], v[112:115]
	v_mfma_f32_16x16x32_bf16 v[104:107], v[140:143], v[202:205], v[104:107]
	v_mfma_f32_16x16x32_bf16 v[96:99], v[132:135], v[210:213], v[96:99]
	v_mfma_f32_16x16x32_bf16 v[88:91], v[140:143], v[210:213], v[88:91]
	v_mfma_f32_16x16x32_bf16 v[80:83], v[132:135], v[218:221], v[80:83]
	v_mfma_f32_16x16x32_bf16 v[72:75], v[140:143], v[218:221], v[72:75]
	v_mfma_f32_16x16x32_bf16 v[116:119], v[162:165], v[186:189], v[116:119]
	v_mfma_f32_16x16x32_bf16 v[108:111], v[178:181], v[186:189], v[108:111]
	v_mfma_f32_16x16x32_bf16 v[100:103], v[162:165], v[198:201], v[100:103]
	v_mfma_f32_16x16x32_bf16 v[92:95], v[178:181], v[198:201], v[92:95]
	v_mfma_f32_16x16x32_bf16 v[84:87], v[162:165], v[206:209], v[84:87]
	v_mfma_f32_16x16x32_bf16 v[76:79], v[178:181], v[206:209], v[76:79]
	v_mfma_f32_16x16x32_bf16 v[68:71], v[162:165], v[214:217], v[68:71]
	v_mfma_f32_16x16x32_bf16 v[64:67], v[178:181], v[214:217], v[64:67]
	v_mfma_f32_16x16x32_bf16 v[116:119], v[174:177], v[194:197], v[116:119]
	v_mfma_f32_16x16x32_bf16 v[108:111], v[182:185], v[194:197], v[108:111]
	v_mfma_f32_16x16x32_bf16 v[100:103], v[174:177], v[202:205], v[100:103]
	v_mfma_f32_16x16x32_bf16 v[92:95], v[182:185], v[202:205], v[92:95]
	v_mfma_f32_16x16x32_bf16 v[84:87], v[174:177], v[210:213], v[84:87]
	v_mfma_f32_16x16x32_bf16 v[76:79], v[182:185], v[210:213], v[76:79]
	v_mfma_f32_16x16x32_bf16 v[68:71], v[174:177], v[218:221], v[68:71]
	v_mfma_f32_16x16x32_bf16 v[64:67], v[182:185], v[218:221], v[64:67]
	s_setprio 0
	s_barrier
	s_add_i32 s26, s54, s3
	v_lshl_add_u64 v[166:167], v[166:167], 0, s[10:11]
	s_mov_b32 m0, s26
	ds_read_b128 v[186:189], v173 offset:49152
	ds_read_b128 v[194:197], v173 offset:50176
	ds_read_b128 v[198:201], v173 offset:51200
	ds_read_b128 v[202:205], v173 offset:52224
	ds_read_b128 v[206:209], v173 offset:53248
	ds_read_b128 v[210:213], v173 offset:54272
	ds_read_b128 v[214:217], v173 offset:55296
	ds_read_b128 v[218:221], v173 offset:56320
	global_load_lds_dwordx4 v[166:167], off
	s_add_i32 m0, s26, 0x2000
	s_add_u32 s26, s30, 0xb0080
	v_lshl_add_u64 v[166:167], v[190:191], 0, s[10:11]
	s_addc_u32 s27, s31, 0
	s_add_i32 s30, s55, s3
	global_load_lds_dwordx4 v[166:167], off
	v_lshl_add_u64 v[166:167], s[26:27], 0, v[148:149]
	s_mov_b32 m0, s30
	s_nop 0
	global_load_lds_dwordx4 v[166:167], off
	v_lshl_add_u64 v[166:167], s[26:27], 0, v[152:153]
	s_add_i32 m0, s30, 0x2000
	s_nop 0
	global_load_lds_dwordx4 v[166:167], off
	v_lshl_add_u64 v[166:167], v[222:223], 0, s[10:11]
	s_mov_b32 m0, s41
	s_nop 0
	global_load_lds_dwordx4 v[166:167], off
	v_lshl_add_u64 v[166:167], v[224:225], 0, s[10:11]
	s_mov_b32 m0, s42
	s_nop 0
	global_load_lds_dwordx4 v[166:167], off
	s_waitcnt vmcnt(8)
	s_waitcnt lgkmcnt(0)
	s_barrier
	s_setprio 1
	s_waitcnt lgkmcnt(0)
	v_mfma_f32_16x16x32_bf16 v[60:63], v[128:131], v[186:189], v[60:63]
	v_mfma_f32_16x16x32_bf16 v[56:59], v[136:139], v[186:189], v[56:59]
	v_mfma_f32_16x16x32_bf16 v[48:51], v[128:131], v[198:201], v[48:51]
	v_mfma_f32_16x16x32_bf16 v[32:35], v[136:139], v[198:201], v[32:35]
	v_mfma_f32_16x16x32_bf16 v[16:19], v[128:131], v[206:209], v[16:19]
	v_mfma_f32_16x16x32_bf16 v[12:15], v[136:139], v[206:209], v[12:15]
	v_mfma_f32_16x16x32_bf16 v[4:7], v[128:131], v[214:217], v[4:7]
	v_mfma_f32_16x16x32_bf16 v[0:3], v[136:139], v[214:217], v[0:3]
	v_mfma_f32_16x16x32_bf16 v[60:63], v[132:135], v[194:197], v[60:63]
	v_mfma_f32_16x16x32_bf16 v[56:59], v[140:143], v[194:197], v[56:59]
	v_mfma_f32_16x16x32_bf16 v[48:51], v[132:135], v[202:205], v[48:51]
	v_mfma_f32_16x16x32_bf16 v[32:35], v[140:143], v[202:205], v[32:35]
	v_mfma_f32_16x16x32_bf16 v[16:19], v[132:135], v[210:213], v[16:19]
	v_mfma_f32_16x16x32_bf16 v[12:15], v[140:143], v[210:213], v[12:15]
	v_mfma_f32_16x16x32_bf16 v[4:7], v[132:135], v[218:221], v[4:7]
	v_mfma_f32_16x16x32_bf16 v[0:3], v[140:143], v[218:221], v[0:3]
	v_mfma_f32_16x16x32_bf16 v[52:55], v[162:165], v[186:189], v[52:55]
	v_mfma_f32_16x16x32_bf16 v[36:39], v[178:181], v[186:189], v[36:39]
	v_mfma_f32_16x16x32_bf16 v[20:23], v[162:165], v[198:201], v[20:23]
	v_mfma_f32_16x16x32_bf16 v[8:11], v[178:181], v[198:201], v[8:11]
	v_mfma_f32_16x16x32_bf16 v[44:47], v[162:165], v[206:209], v[44:47]
	v_mfma_f32_16x16x32_bf16 v[40:43], v[178:181], v[206:209], v[40:43]
	v_mfma_f32_16x16x32_bf16 v[28:31], v[162:165], v[214:217], v[28:31]
	v_mfma_f32_16x16x32_bf16 v[24:27], v[178:181], v[214:217], v[24:27]
	v_mfma_f32_16x16x32_bf16 v[52:55], v[174:177], v[194:197], v[52:55]
	v_mfma_f32_16x16x32_bf16 v[36:39], v[182:185], v[194:197], v[36:39]
	v_mfma_f32_16x16x32_bf16 v[20:23], v[174:177], v[202:205], v[20:23]
	v_mfma_f32_16x16x32_bf16 v[8:11], v[182:185], v[202:205], v[8:11]
	v_mfma_f32_16x16x32_bf16 v[44:47], v[174:177], v[210:213], v[44:47]
	v_mfma_f32_16x16x32_bf16 v[40:43], v[182:185], v[210:213], v[40:43]
	v_mfma_f32_16x16x32_bf16 v[28:31], v[174:177], v[218:221], v[28:31]
	v_mfma_f32_16x16x32_bf16 v[24:27], v[182:185], v[218:221], v[24:27]
	s_setprio 0
	s_barrier
	s_add_i32 s53, s53, 2
	s_add_u32 s51, s51, 0x100
	s_addc_u32 s52, s52, 0
	s_cmp_gt_u32 s53, 41
	s_mov_b64 s[26:27], s[28:29]
	s_cbranch_scc0 .LBB0_1177
	s_and_b64 vcc, exec, s[12:13]
	s_cbranch_vccz .LBB0_1180
	s_barrier
